# PEER up: last reduction stage (xor 8) via DPP row_shl/shr:8 bank-masked adds; no ds_bpermute left in up/down2 math
# baseline (speedup 1.0000x reference)
; DI void up_math(const u32x4 (&W)[16], const u32 (&pj)[16], float* __restrict__ yrow, int lane) {
;   f2 y[8];
; #pragma unroll
;   for (int i = 0; i < 8; ++i) y[i] = f2{0.f, 0.f};
; #pragma unroll
;   for (int j = 0; j < 16; ++j) {
;     const float h = __uint_as_float(pj[j] << 16);
;     const f2 hh = {h, h};
; #pragma unroll
;     for (int d = 0; d < 4; ++d) {
;       f2 lo = __builtin_amdgcn_cvt_pk_f32_fp8((int)W[j][d], false);
;       f2 hi = __builtin_amdgcn_cvt_pk_f32_fp8((int)W[j][d], true);
;       y[2 * d] = lo * hh + y[2 * d];
;       y[2 * d + 1] = hi * hh + y[2 * d + 1];
;     }
;   }
.LBB0_826:
	s_add_i32 s44, s44, 2
	s_waitcnt vmcnt(16)
	v_cvt_pk_f32_fp8_e32 v[216:217], v128
	v_cvt_pk_f32_fp8_sdwa v[226:227], v128 src0_sel:WORD_1
	v_cvt_pk_f32_fp8_e32 v[228:229], v129
	v_cvt_pk_f32_fp8_sdwa v[128:129], v129 src0_sel:WORD_1
	v_cvt_pk_f32_fp8_e32 v[230:231], v130
	v_cvt_pk_f32_fp8_sdwa v[232:233], v130 src0_sel:WORD_1
	v_cvt_pk_f32_fp8_e32 v[234:235], v131
	v_cvt_pk_f32_fp8_sdwa v[130:131], v131 src0_sel:WORD_1
	v_lshlrev_b32_e32 v132, 16, v210
	v_pk_fma_f32 v[216:217], v[132:133], v[216:217], 0 op_sel_hi:[0,1,0]
	v_pk_fma_f32 v[226:227], v[132:133], v[226:227], 0 op_sel_hi:[0,1,0]
	v_pk_fma_f32 v[228:229], v[132:133], v[228:229], 0 op_sel_hi:[0,1,0]
	v_pk_fma_f32 v[128:129], v[132:133], v[128:129], 0 op_sel_hi:[0,1,0]
	v_pk_fma_f32 v[230:231], v[132:133], v[230:231], 0 op_sel_hi:[0,1,0]
	v_pk_fma_f32 v[232:233], v[132:133], v[232:233], 0 op_sel_hi:[0,1,0]
	v_pk_fma_f32 v[234:235], v[132:133], v[234:235], 0 op_sel_hi:[0,1,0]
	v_pk_fma_f32 v[130:131], v[132:133], v[130:131], 0 op_sel_hi:[0,1,0]
	v_lshlrev_b32_e32 v132, 16, v211
	s_waitcnt vmcnt(15)
	v_cvt_pk_f32_fp8_e32 v[210:211], v124
	v_cvt_pk_f32_fp8_sdwa v[236:237], v124 src0_sel:WORD_1
	v_cvt_pk_f32_fp8_e32 v[238:239], v125
	v_cvt_pk_f32_fp8_sdwa v[124:125], v125 src0_sel:WORD_1
	v_pk_fma_f32 v[210:211], v[132:133], v[210:211], v[216:217] op_sel_hi:[0,1,1]
	v_pk_fma_f32 v[216:217], v[132:133], v[236:237], v[226:227] op_sel_hi:[0,1,1]
	v_pk_fma_f32 v[226:227], v[132:133], v[238:239], v[228:229] op_sel_hi:[0,1,1]
	v_pk_fma_f32 v[124:125], v[132:133], v[124:125], v[128:129] op_sel_hi:[0,1,1]
	v_cvt_pk_f32_fp8_e32 v[128:129], v126
	v_cvt_pk_f32_fp8_sdwa v[228:229], v126 src0_sel:WORD_1
	v_cvt_pk_f32_fp8_e32 v[236:237], v127
	v_cvt_pk_f32_fp8_sdwa v[126:127], v127 src0_sel:WORD_1
	v_pk_fma_f32 v[128:129], v[132:133], v[128:129], v[230:231] op_sel_hi:[0,1,1]
	v_pk_fma_f32 v[228:229], v[132:133], v[228:229], v[232:233] op_sel_hi:[0,1,1]
	v_pk_fma_f32 v[230:231], v[132:133], v[236:237], v[234:235] op_sel_hi:[0,1,1]
	s_waitcnt vmcnt(14)
	v_cvt_pk_f32_fp8_e32 v[232:233], v120
	v_cvt_pk_f32_fp8_sdwa v[234:235], v120 src0_sel:WORD_1
	v_cvt_pk_f32_fp8_e32 v[236:237], v121
	v_cvt_pk_f32_fp8_sdwa v[120:121], v121 src0_sel:WORD_1
	v_pk_fma_f32 v[126:127], v[132:133], v[126:127], v[130:131] op_sel_hi:[0,1,1]
	v_lshlrev_b32_e32 v130, 16, v208
	v_pk_fma_f32 v[210:211], v[130:131], v[232:233], v[210:211] op_sel_hi:[0,1,1]
	v_pk_fma_f32 v[216:217], v[130:131], v[234:235], v[216:217] op_sel_hi:[0,1,1]
	v_pk_fma_f32 v[120:121], v[130:131], v[120:121], v[124:125] op_sel_hi:[0,1,1]
	v_cvt_pk_f32_fp8_e32 v[124:125], v122
	v_cvt_pk_f32_fp8_sdwa v[232:233], v122 src0_sel:WORD_1
	v_cvt_pk_f32_fp8_e32 v[234:235], v123
	v_cvt_pk_f32_fp8_sdwa v[122:123], v123 src0_sel:WORD_1
	v_pk_fma_f32 v[226:227], v[130:131], v[236:237], v[226:227] op_sel_hi:[0,1,1]
	v_pk_fma_f32 v[124:125], v[130:131], v[124:125], v[128:129] op_sel_hi:[0,1,1]
	v_pk_fma_f32 v[128:129], v[130:131], v[232:233], v[228:229] op_sel_hi:[0,1,1]
	v_pk_fma_f32 v[228:229], v[130:131], v[234:235], v[230:231] op_sel_hi:[0,1,1]
	v_pk_fma_f32 v[122:123], v[130:131], v[122:123], v[126:127] op_sel_hi:[0,1,1]
	v_lshlrev_b32_e32 v126, 16, v209
	s_waitcnt vmcnt(13)
	v_cvt_pk_f32_fp8_e32 v[130:131], v116
	v_cvt_pk_f32_fp8_sdwa v[208:209], v116 src0_sel:WORD_1
	v_cvt_pk_f32_fp8_e32 v[230:231], v117
	v_cvt_pk_f32_fp8_sdwa v[116:117], v117 src0_sel:WORD_1
	v_pk_fma_f32 v[130:131], v[126:127], v[130:131], v[210:211] op_sel_hi:[0,1,1]
	v_pk_fma_f32 v[208:209], v[126:127], v[208:209], v[216:217] op_sel_hi:[0,1,1]
	v_pk_fma_f32 v[210:211], v[126:127], v[230:231], v[226:227] op_sel_hi:[0,1,1]
	v_pk_fma_f32 v[116:117], v[126:127], v[116:117], v[120:121] op_sel_hi:[0,1,1]
	v_cvt_pk_f32_fp8_e32 v[120:121], v118
	v_cvt_pk_f32_fp8_sdwa v[216:217], v118 src0_sel:WORD_1
	v_cvt_pk_f32_fp8_e32 v[226:227], v119
	v_cvt_pk_f32_fp8_sdwa v[118:119], v119 src0_sel:WORD_1
	v_pk_fma_f32 v[120:121], v[126:127], v[120:121], v[124:125] op_sel_hi:[0,1,1]
	v_pk_fma_f32 v[124:125], v[126:127], v[216:217], v[128:129] op_sel_hi:[0,1,1]
	v_pk_fma_f32 v[128:129], v[126:127], v[226:227], v[228:229] op_sel_hi:[0,1,1]
	v_pk_fma_f32 v[118:119], v[126:127], v[118:119], v[122:123] op_sel_hi:[0,1,1]
	s_waitcnt vmcnt(12)
	v_cvt_pk_f32_fp8_e32 v[126:127], v112
	v_cvt_pk_f32_fp8_sdwa v[216:217], v112 src0_sel:WORD_1
	v_cvt_pk_f32_fp8_e32 v[226:227], v113
	v_cvt_pk_f32_fp8_sdwa v[112:113], v113 src0_sel:WORD_1
	v_lshlrev_b32_e32 v122, 16, v206
	v_pk_fma_f32 v[126:127], v[122:123], v[126:127], v[130:131] op_sel_hi:[0,1,1]
	v_pk_fma_f32 v[130:131], v[122:123], v[216:217], v[208:209] op_sel_hi:[0,1,1]
	v_pk_fma_f32 v[208:209], v[122:123], v[226:227], v[210:211] op_sel_hi:[0,1,1]
	v_pk_fma_f32 v[112:113], v[122:123], v[112:113], v[116:117] op_sel_hi:[0,1,1]
	v_cvt_pk_f32_fp8_e32 v[116:117], v114
	v_cvt_pk_f32_fp8_sdwa v[210:211], v114 src0_sel:WORD_1
	v_cvt_pk_f32_fp8_e32 v[216:217], v115
	v_cvt_pk_f32_fp8_sdwa v[114:115], v115 src0_sel:WORD_1
	v_pk_fma_f32 v[116:117], v[122:123], v[116:117], v[120:121] op_sel_hi:[0,1,1]
	v_pk_fma_f32 v[120:121], v[122:123], v[210:211], v[124:125] op_sel_hi:[0,1,1]
	v_pk_fma_f32 v[124:125], v[122:123], v[216:217], v[128:129] op_sel_hi:[0,1,1]
	v_pk_fma_f32 v[114:115], v[122:123], v[114:115], v[118:119] op_sel_hi:[0,1,1]
	v_lshlrev_b32_e32 v118, 16, v207
	s_waitcnt vmcnt(11)
; DI void up_math(const u32x4 (&W)[16], const u32 (&pj)[16], float* __restrict__ yrow, int lane) {
;     ...
;   for (int j = 0; j < 16; ++j) {
;     const float h = __uint_as_float(pj[j] << 16);
;     const f2 hh = {h, h};
; #pragma unroll
;     for (int d = 0; d < 4; ++d) {
;       f2 lo = __builtin_amdgcn_cvt_pk_f32_fp8((int)W[j][d], false);
;       f2 hi = __builtin_amdgcn_cvt_pk_f32_fp8((int)W[j][d], true);
;       y[2 * d] = lo * hh + y[2 * d];
;       y[2 * d + 1] = hi * hh + y[2 * d + 1];
;     }
;   }
	v_cvt_pk_f32_fp8_e32 v[122:123], v108
	v_cvt_pk_f32_fp8_sdwa v[128:129], v108 src0_sel:WORD_1
	v_cvt_pk_f32_fp8_e32 v[206:207], v109
	v_cvt_pk_f32_fp8_sdwa v[108:109], v109 src0_sel:WORD_1
	v_pk_fma_f32 v[122:123], v[118:119], v[122:123], v[126:127] op_sel_hi:[0,1,1]
	v_pk_fma_f32 v[126:127], v[118:119], v[128:129], v[130:131] op_sel_hi:[0,1,1]
	v_pk_fma_f32 v[128:129], v[118:119], v[206:207], v[208:209] op_sel_hi:[0,1,1]
	v_pk_fma_f32 v[108:109], v[118:119], v[108:109], v[112:113] op_sel_hi:[0,1,1]
	v_cvt_pk_f32_fp8_e32 v[112:113], v110
	v_cvt_pk_f32_fp8_sdwa v[130:131], v110 src0_sel:WORD_1
	v_cvt_pk_f32_fp8_e32 v[206:207], v111
	v_cvt_pk_f32_fp8_sdwa v[110:111], v111 src0_sel:WORD_1
	v_pk_fma_f32 v[112:113], v[118:119], v[112:113], v[116:117] op_sel_hi:[0,1,1]
	v_pk_fma_f32 v[116:117], v[118:119], v[130:131], v[120:121] op_sel_hi:[0,1,1]
	v_pk_fma_f32 v[120:121], v[118:119], v[206:207], v[124:125] op_sel_hi:[0,1,1]
	v_pk_fma_f32 v[110:111], v[118:119], v[110:111], v[114:115] op_sel_hi:[0,1,1]
	s_waitcnt vmcnt(10)
	v_cvt_pk_f32_fp8_e32 v[118:119], v104
	v_cvt_pk_f32_fp8_sdwa v[124:125], v104 src0_sel:WORD_1
	v_cvt_pk_f32_fp8_e32 v[130:131], v105
	v_cvt_pk_f32_fp8_sdwa v[104:105], v105 src0_sel:WORD_1
	v_lshlrev_b32_e32 v114, 16, v204
	v_pk_fma_f32 v[118:119], v[114:115], v[118:119], v[122:123] op_sel_hi:[0,1,1]
	v_pk_fma_f32 v[122:123], v[114:115], v[124:125], v[126:127] op_sel_hi:[0,1,1]
	v_pk_fma_f32 v[124:125], v[114:115], v[130:131], v[128:129] op_sel_hi:[0,1,1]
	v_pk_fma_f32 v[104:105], v[114:115], v[104:105], v[108:109] op_sel_hi:[0,1,1]
	v_cvt_pk_f32_fp8_e32 v[108:109], v106
	v_cvt_pk_f32_fp8_sdwa v[126:127], v106 src0_sel:WORD_1
	v_cvt_pk_f32_fp8_e32 v[128:129], v107
	v_cvt_pk_f32_fp8_sdwa v[106:107], v107 src0_sel:WORD_1
	v_pk_fma_f32 v[108:109], v[114:115], v[108:109], v[112:113] op_sel_hi:[0,1,1]
	v_pk_fma_f32 v[112:113], v[114:115], v[126:127], v[116:117] op_sel_hi:[0,1,1]
	v_pk_fma_f32 v[116:117], v[114:115], v[128:129], v[120:121] op_sel_hi:[0,1,1]
	v_pk_fma_f32 v[106:107], v[114:115], v[106:107], v[110:111] op_sel_hi:[0,1,1]
	s_waitcnt vmcnt(9)
	v_cvt_pk_f32_fp8_e32 v[114:115], v100
	v_cvt_pk_f32_fp8_sdwa v[120:121], v100 src0_sel:WORD_1
	v_cvt_pk_f32_fp8_e32 v[126:127], v101
	v_cvt_pk_f32_fp8_sdwa v[100:101], v101 src0_sel:WORD_1
	v_lshlrev_b32_e32 v110, 16, v205
	v_pk_fma_f32 v[114:115], v[110:111], v[114:115], v[118:119] op_sel_hi:[0,1,1]
	v_pk_fma_f32 v[118:119], v[110:111], v[120:121], v[122:123] op_sel_hi:[0,1,1]
	v_pk_fma_f32 v[120:121], v[110:111], v[126:127], v[124:125] op_sel_hi:[0,1,1]
	v_pk_fma_f32 v[100:101], v[110:111], v[100:101], v[104:105] op_sel_hi:[0,1,1]
	v_cvt_pk_f32_fp8_e32 v[104:105], v102
	v_cvt_pk_f32_fp8_sdwa v[122:123], v102 src0_sel:WORD_1
	v_cvt_pk_f32_fp8_e32 v[124:125], v103
	v_cvt_pk_f32_fp8_sdwa v[102:103], v103 src0_sel:WORD_1
	v_pk_fma_f32 v[104:105], v[110:111], v[104:105], v[108:109] op_sel_hi:[0,1,1]
	v_pk_fma_f32 v[108:109], v[110:111], v[122:123], v[112:113] op_sel_hi:[0,1,1]
	v_pk_fma_f32 v[112:113], v[110:111], v[124:125], v[116:117] op_sel_hi:[0,1,1]
	v_pk_fma_f32 v[102:103], v[110:111], v[102:103], v[106:107] op_sel_hi:[0,1,1]
	s_waitcnt vmcnt(8)
	v_cvt_pk_f32_fp8_e32 v[110:111], v96
	v_cvt_pk_f32_fp8_sdwa v[116:117], v96 src0_sel:WORD_1
	v_cvt_pk_f32_fp8_e32 v[122:123], v97
	v_cvt_pk_f32_fp8_sdwa v[96:97], v97 src0_sel:WORD_1
	v_lshlrev_b32_e32 v106, 16, v202
	v_pk_fma_f32 v[110:111], v[106:107], v[110:111], v[114:115] op_sel_hi:[0,1,1]
	v_pk_fma_f32 v[114:115], v[106:107], v[116:117], v[118:119] op_sel_hi:[0,1,1]
	v_pk_fma_f32 v[116:117], v[106:107], v[122:123], v[120:121] op_sel_hi:[0,1,1]
	v_pk_fma_f32 v[96:97], v[106:107], v[96:97], v[100:101] op_sel_hi:[0,1,1]
	v_cvt_pk_f32_fp8_e32 v[100:101], v98
	v_cvt_pk_f32_fp8_sdwa v[118:119], v98 src0_sel:WORD_1
	v_cvt_pk_f32_fp8_e32 v[120:121], v99
	v_cvt_pk_f32_fp8_sdwa v[98:99], v99 src0_sel:WORD_1
	v_pk_fma_f32 v[100:101], v[106:107], v[100:101], v[104:105] op_sel_hi:[0,1,1]
	v_pk_fma_f32 v[104:105], v[106:107], v[118:119], v[108:109] op_sel_hi:[0,1,1]
	v_pk_fma_f32 v[108:109], v[106:107], v[120:121], v[112:113] op_sel_hi:[0,1,1]
	v_pk_fma_f32 v[98:99], v[106:107], v[98:99], v[102:103] op_sel_hi:[0,1,1]
	s_waitcnt vmcnt(7)
	v_cvt_pk_f32_fp8_e32 v[106:107], v92
	v_cvt_pk_f32_fp8_sdwa v[112:113], v92 src0_sel:WORD_1
	v_cvt_pk_f32_fp8_e32 v[118:119], v93
	v_cvt_pk_f32_fp8_sdwa v[92:93], v93 src0_sel:WORD_1
	v_lshlrev_b32_e32 v102, 16, v203
	v_pk_fma_f32 v[106:107], v[102:103], v[106:107], v[110:111] op_sel_hi:[0,1,1]
	v_pk_fma_f32 v[110:111], v[102:103], v[112:113], v[114:115] op_sel_hi:[0,1,1]
	v_pk_fma_f32 v[112:113], v[102:103], v[118:119], v[116:117] op_sel_hi:[0,1,1]
	v_pk_fma_f32 v[92:93], v[102:103], v[92:93], v[96:97] op_sel_hi:[0,1,1]
	v_cvt_pk_f32_fp8_e32 v[96:97], v94
	v_cvt_pk_f32_fp8_sdwa v[114:115], v94 src0_sel:WORD_1
	v_cvt_pk_f32_fp8_e32 v[116:117], v95
	v_cvt_pk_f32_fp8_sdwa v[94:95], v95 src0_sel:WORD_1
	v_pk_fma_f32 v[96:97], v[102:103], v[96:97], v[100:101] op_sel_hi:[0,1,1]
	v_pk_fma_f32 v[100:101], v[102:103], v[114:115], v[104:105] op_sel_hi:[0,1,1]
	v_pk_fma_f32 v[104:105], v[102:103], v[116:117], v[108:109] op_sel_hi:[0,1,1]
	v_pk_fma_f32 v[94:95], v[102:103], v[94:95], v[98:99] op_sel_hi:[0,1,1]
	s_waitcnt vmcnt(6)
; DI void up_math(const u32x4 (&W)[16], const u32 (&pj)[16], float* __restrict__ yrow, int lane) {
;     ...
;   for (int j = 0; j < 16; ++j) {
;     const float h = __uint_as_float(pj[j] << 16);
;     const f2 hh = {h, h};
; #pragma unroll
;     for (int d = 0; d < 4; ++d) {
;       f2 lo = __builtin_amdgcn_cvt_pk_f32_fp8((int)W[j][d], false);
;       f2 hi = __builtin_amdgcn_cvt_pk_f32_fp8((int)W[j][d], true);
;       y[2 * d] = lo * hh + y[2 * d];
;       y[2 * d + 1] = hi * hh + y[2 * d + 1];
;     }
;   }
	v_cvt_pk_f32_fp8_e32 v[102:103], v88
	v_cvt_pk_f32_fp8_sdwa v[108:109], v88 src0_sel:WORD_1
	v_cvt_pk_f32_fp8_e32 v[114:115], v89
	v_cvt_pk_f32_fp8_sdwa v[88:89], v89 src0_sel:WORD_1
	v_lshlrev_b32_e32 v98, 16, v200
	v_pk_fma_f32 v[102:103], v[98:99], v[102:103], v[106:107] op_sel_hi:[0,1,1]
	v_pk_fma_f32 v[106:107], v[98:99], v[108:109], v[110:111] op_sel_hi:[0,1,1]
	v_pk_fma_f32 v[108:109], v[98:99], v[114:115], v[112:113] op_sel_hi:[0,1,1]
	v_pk_fma_f32 v[88:89], v[98:99], v[88:89], v[92:93] op_sel_hi:[0,1,1]
	v_cvt_pk_f32_fp8_e32 v[92:93], v90
	v_cvt_pk_f32_fp8_sdwa v[110:111], v90 src0_sel:WORD_1
	v_cvt_pk_f32_fp8_e32 v[112:113], v91
	v_cvt_pk_f32_fp8_sdwa v[90:91], v91 src0_sel:WORD_1
	v_pk_fma_f32 v[92:93], v[98:99], v[92:93], v[96:97] op_sel_hi:[0,1,1]
	v_pk_fma_f32 v[96:97], v[98:99], v[110:111], v[100:101] op_sel_hi:[0,1,1]
	v_pk_fma_f32 v[100:101], v[98:99], v[112:113], v[104:105] op_sel_hi:[0,1,1]
	v_pk_fma_f32 v[90:91], v[98:99], v[90:91], v[94:95] op_sel_hi:[0,1,1]
	s_waitcnt vmcnt(5)
	v_cvt_pk_f32_fp8_e32 v[98:99], v84
	v_cvt_pk_f32_fp8_sdwa v[104:105], v84 src0_sel:WORD_1
	v_cvt_pk_f32_fp8_e32 v[110:111], v85
	v_cvt_pk_f32_fp8_sdwa v[84:85], v85 src0_sel:WORD_1
	v_lshlrev_b32_e32 v94, 16, v201
	v_pk_fma_f32 v[98:99], v[94:95], v[98:99], v[102:103] op_sel_hi:[0,1,1]
	v_pk_fma_f32 v[102:103], v[94:95], v[104:105], v[106:107] op_sel_hi:[0,1,1]
	v_pk_fma_f32 v[104:105], v[94:95], v[110:111], v[108:109] op_sel_hi:[0,1,1]
	v_pk_fma_f32 v[84:85], v[94:95], v[84:85], v[88:89] op_sel_hi:[0,1,1]
	v_cvt_pk_f32_fp8_e32 v[88:89], v86
	v_cvt_pk_f32_fp8_sdwa v[106:107], v86 src0_sel:WORD_1
	v_cvt_pk_f32_fp8_e32 v[108:109], v87
	v_cvt_pk_f32_fp8_sdwa v[86:87], v87 src0_sel:WORD_1
	v_pk_fma_f32 v[88:89], v[94:95], v[88:89], v[92:93] op_sel_hi:[0,1,1]
	v_pk_fma_f32 v[92:93], v[94:95], v[106:107], v[96:97] op_sel_hi:[0,1,1]
	v_pk_fma_f32 v[96:97], v[94:95], v[108:109], v[100:101] op_sel_hi:[0,1,1]
	v_pk_fma_f32 v[86:87], v[94:95], v[86:87], v[90:91] op_sel_hi:[0,1,1]
	s_waitcnt vmcnt(4)
	v_cvt_pk_f32_fp8_e32 v[94:95], v80
	v_cvt_pk_f32_fp8_sdwa v[100:101], v80 src0_sel:WORD_1
	v_cvt_pk_f32_fp8_e32 v[106:107], v81
	v_cvt_pk_f32_fp8_sdwa v[80:81], v81 src0_sel:WORD_1
	v_lshlrev_b32_e32 v90, 16, v198
	v_pk_fma_f32 v[94:95], v[90:91], v[94:95], v[98:99] op_sel_hi:[0,1,1]
	v_pk_fma_f32 v[98:99], v[90:91], v[100:101], v[102:103] op_sel_hi:[0,1,1]
	v_pk_fma_f32 v[100:101], v[90:91], v[106:107], v[104:105] op_sel_hi:[0,1,1]
	v_pk_fma_f32 v[80:81], v[90:91], v[80:81], v[84:85] op_sel_hi:[0,1,1]
	v_cvt_pk_f32_fp8_e32 v[84:85], v82
	v_cvt_pk_f32_fp8_sdwa v[102:103], v82 src0_sel:WORD_1
	v_cvt_pk_f32_fp8_e32 v[104:105], v83
	v_cvt_pk_f32_fp8_sdwa v[82:83], v83 src0_sel:WORD_1
	v_pk_fma_f32 v[84:85], v[90:91], v[84:85], v[88:89] op_sel_hi:[0,1,1]
	v_pk_fma_f32 v[88:89], v[90:91], v[102:103], v[92:93] op_sel_hi:[0,1,1]
	v_pk_fma_f32 v[92:93], v[90:91], v[104:105], v[96:97] op_sel_hi:[0,1,1]
	v_pk_fma_f32 v[82:83], v[90:91], v[82:83], v[86:87] op_sel_hi:[0,1,1]
	s_waitcnt vmcnt(3)
	v_cvt_pk_f32_fp8_e32 v[90:91], v76
	v_cvt_pk_f32_fp8_sdwa v[96:97], v76 src0_sel:WORD_1
	v_cvt_pk_f32_fp8_e32 v[102:103], v77
	v_cvt_pk_f32_fp8_sdwa v[76:77], v77 src0_sel:WORD_1
	v_lshlrev_b32_e32 v86, 16, v199
	v_pk_fma_f32 v[90:91], v[86:87], v[90:91], v[94:95] op_sel_hi:[0,1,1]
	v_pk_fma_f32 v[94:95], v[86:87], v[96:97], v[98:99] op_sel_hi:[0,1,1]
	v_pk_fma_f32 v[96:97], v[86:87], v[102:103], v[100:101] op_sel_hi:[0,1,1]
	v_pk_fma_f32 v[76:77], v[86:87], v[76:77], v[80:81] op_sel_hi:[0,1,1]
	v_cvt_pk_f32_fp8_e32 v[80:81], v78
	v_cvt_pk_f32_fp8_sdwa v[98:99], v78 src0_sel:WORD_1
	v_cvt_pk_f32_fp8_e32 v[100:101], v79
	v_cvt_pk_f32_fp8_sdwa v[78:79], v79 src0_sel:WORD_1
	v_pk_fma_f32 v[80:81], v[86:87], v[80:81], v[84:85] op_sel_hi:[0,1,1]
	v_pk_fma_f32 v[84:85], v[86:87], v[98:99], v[88:89] op_sel_hi:[0,1,1]
	v_pk_fma_f32 v[88:89], v[86:87], v[100:101], v[92:93] op_sel_hi:[0,1,1]
	v_pk_fma_f32 v[78:79], v[86:87], v[78:79], v[82:83] op_sel_hi:[0,1,1]
	s_waitcnt vmcnt(2)
	v_cvt_pk_f32_fp8_e32 v[86:87], v72
	v_cvt_pk_f32_fp8_sdwa v[92:93], v72 src0_sel:WORD_1
	v_cvt_pk_f32_fp8_e32 v[98:99], v73
	v_cvt_pk_f32_fp8_sdwa v[72:73], v73 src0_sel:WORD_1
	v_lshlrev_b32_e32 v82, 16, v196
	v_pk_fma_f32 v[86:87], v[82:83], v[86:87], v[90:91] op_sel_hi:[0,1,1]
	v_pk_fma_f32 v[90:91], v[82:83], v[92:93], v[94:95] op_sel_hi:[0,1,1]
	v_pk_fma_f32 v[92:93], v[82:83], v[98:99], v[96:97] op_sel_hi:[0,1,1]
	v_pk_fma_f32 v[72:73], v[82:83], v[72:73], v[76:77] op_sel_hi:[0,1,1]
	v_cvt_pk_f32_fp8_e32 v[76:77], v74
	v_cvt_pk_f32_fp8_sdwa v[94:95], v74 src0_sel:WORD_1
	v_cvt_pk_f32_fp8_e32 v[96:97], v75
	v_cvt_pk_f32_fp8_sdwa v[74:75], v75 src0_sel:WORD_1
	v_pk_fma_f32 v[76:77], v[82:83], v[76:77], v[80:81] op_sel_hi:[0,1,1]
	v_pk_fma_f32 v[80:81], v[82:83], v[94:95], v[84:85] op_sel_hi:[0,1,1]
	v_pk_fma_f32 v[84:85], v[82:83], v[96:97], v[88:89] op_sel_hi:[0,1,1]
	v_pk_fma_f32 v[74:75], v[82:83], v[74:75], v[78:79] op_sel_hi:[0,1,1]
	s_waitcnt vmcnt(1)
; DI void up_issue(u32x4 (&W)[16], u32 (&pj)[16], const u32* pl, const unsigned char* wbase, int grp) {
; #pragma unroll
;   for (int j = 0; j < 16; ++j) {
;     pj[j] = pl[8 * j + grp];
;     W[j] = *(const u32x4*)(wbase + (size_t)(pj[j] >> 16) * 1024);
;   }
; DI void up_math(const u32x4 (&W)[16], const u32 (&pj)[16], float* __restrict__ yrow, int lane) {
;     ...
;   for (int j = 0; j < 16; ++j) {
;     const float h = __uint_as_float(pj[j] << 16);
;     const f2 hh = {h, h};
; #pragma unroll
;     for (int d = 0; d < 4; ++d) {
;       f2 lo = __builtin_amdgcn_cvt_pk_f32_fp8((int)W[j][d], false);
;       f2 hi = __builtin_amdgcn_cvt_pk_f32_fp8((int)W[j][d], true);
;       y[2 * d] = lo * hh + y[2 * d];
;       y[2 * d + 1] = hi * hh + y[2 * d + 1];
;     }
;   }
;   const bool b5 = lane & 32, b4 = lane & 16, b3 = lane & 8;
;   f2 q4[4];
; #pragma unroll
;   for (int i = 0; i < 4; ++i) {
;     f2 snd = b5 ? y[i] : y[i + 4]; f2 kp = b5 ? y[i + 4] : y[i];
;     q4[i] = f2{kp.x + __shfl_xor(snd.x, 32), kp.y + __shfl_xor(snd.y, 32)};
;   }
;   f2 r2[2];
; #pragma unroll
;   for (int i = 0; i < 2; ++i) {
;     f2 snd = b4 ? q4[i] : q4[i + 2]; f2 kp = b4 ? q4[i + 2] : q4[i];
;     r2[i] = f2{kp.x + __shfl_xor(snd.x, 16), kp.y + __shfl_xor(snd.y, 16)};
;   }
;   f2 a;
;   { f2 snd = b3 ? r2[0] : r2[1]; f2 kp = b3 ? r2[1] : r2[0]; a = f2{kp.x + __shfl_xor(snd.x, 8), kp.y + __shfl_xor(snd.y, 8)}; }
;   const int ci = (b5 ? 4 : 0) + (b4 ? 2 : 0) + (b3 ? 1 : 0);
;   *(float2*)(yrow + (lane & 7) * 16 + 2 * ci) = make_float2(a.x, a.y);
	v_cvt_pk_f32_fp8_e32 v[82:83], v68
	v_cvt_pk_f32_fp8_sdwa v[88:89], v68 src0_sel:WORD_1
	v_cvt_pk_f32_fp8_e32 v[94:95], v69
	v_cvt_pk_f32_fp8_sdwa v[68:69], v69 src0_sel:WORD_1
	v_lshlrev_b32_e32 v78, 16, v197
	v_pk_fma_f32 v[82:83], v[78:79], v[82:83], v[86:87] op_sel_hi:[0,1,1]
	v_pk_fma_f32 v[86:87], v[78:79], v[88:89], v[90:91] op_sel_hi:[0,1,1]
	v_pk_fma_f32 v[68:69], v[78:79], v[68:69], v[72:73] op_sel_hi:[0,1,1]
	v_cvt_pk_f32_fp8_e32 v[72:73], v70
	v_pk_fma_f32 v[88:89], v[78:79], v[94:95], v[92:93] op_sel_hi:[0,1,1]
	v_cvt_pk_f32_fp8_sdwa v[90:91], v70 src0_sel:WORD_1
	v_cvt_pk_f32_fp8_e32 v[92:93], v71
	v_cvt_pk_f32_fp8_sdwa v[70:71], v71 src0_sel:WORD_1
	v_pk_fma_f32 v[72:73], v[78:79], v[72:73], v[76:77] op_sel_hi:[0,1,1]
	v_pk_fma_f32 v[76:77], v[78:79], v[90:91], v[80:81] op_sel_hi:[0,1,1]
	v_pk_fma_f32 v[80:81], v[78:79], v[92:93], v[84:85] op_sel_hi:[0,1,1]
	v_pk_fma_f32 v[70:71], v[78:79], v[70:71], v[74:75] op_sel_hi:[0,1,1]
	s_nop 1
	v_permlane32_swap_b32_e32 v82, v72
	v_permlane32_swap_b32_e32 v83, v73
	v_permlane32_swap_b32_e32 v86, v76
	v_permlane32_swap_b32_e32 v87, v77
	v_permlane32_swap_b32_e32 v88, v80
	v_permlane32_swap_b32_e32 v89, v81
	v_permlane32_swap_b32_e32 v68, v70
	v_permlane32_swap_b32_e32 v69, v71
	v_pk_add_f32 v[72:73], v[82:83], v[72:73]
	v_pk_add_f32 v[74:75], v[86:87], v[76:77]
	v_pk_add_f32 v[76:77], v[88:89], v[80:81]
	v_pk_add_f32 v[68:69], v[68:69], v[70:71]
	s_nop 1
	v_permlane16_swap_b32_e32 v72, v76
	v_permlane16_swap_b32_e32 v73, v77
	v_permlane16_swap_b32_e32 v74, v68
	v_permlane16_swap_b32_e32 v75, v69
	v_pk_add_f32 v[70:71], v[72:73], v[76:77]
	v_pk_add_f32 v[68:69], v[74:75], v[68:69]
	s_nop 1
	v_add_f32_dpp v68, v68, v68 row_shr:8 row_mask:0xf bank_mask:0xc
	v_add_f32_dpp v69, v69, v69 row_shr:8 row_mask:0xf bank_mask:0xc
	v_add_f32_dpp v68, v70, v70 row_shl:8 row_mask:0xf bank_mask:0x3
	v_add_f32_dpp v69, v71, v71 row_shl:8 row_mask:0xf bank_mask:0x3
	v_add_co_u32_e32 v70, vcc, 0x1000, v188
	v_addc_co_u32_e32 v71, vcc, 0, v189, vcc
	global_store_dwordx2 v[70:71], v[68:69], off
	v_add_u32_e32 v145, 0x400, v145
	v_lshl_add_u64 v[188:189], v[188:189], 0, s[40:41]
	s_and_b64 vcc, exec, s[28:29]
	s_cbranch_vccnz .LBB0_814
.LBB0_827:
	ds_read2_b32 v[210:211], v145 offset1:8
	ds_read2_b32 v[208:209], v145 offset0:16 offset1:24
	s_waitcnt lgkmcnt(1)
	v_lshlrev_b32_sdwa v132, v215, v210 dst_sel:DWORD dst_unused:UNUSED_PAD src0_sel:DWORD src1_sel:WORD_1
	v_lshl_add_u64 v[68:69], v[174:175], 0, v[132:133]
	v_lshlrev_b32_sdwa v132, v215, v211 dst_sel:DWORD dst_unused:UNUSED_PAD src0_sel:DWORD src1_sel:WORD_1
	v_lshl_add_u64 v[70:71], v[174:175], 0, v[132:133]
	s_waitcnt lgkmcnt(0)
	v_lshlrev_b32_sdwa v132, v215, v208 dst_sel:DWORD dst_unused:UNUSED_PAD src0_sel:DWORD src1_sel:WORD_1
	global_load_dwordx4 v[128:131], v[68:69], off
	global_load_dwordx4 v[124:127], v[70:71], off
	ds_read2_b32 v[206:207], v145 offset0:32 offset1:40
	v_lshl_add_u64 v[68:69], v[174:175], 0, v[132:133]
	v_lshlrev_b32_sdwa v132, v215, v209 dst_sel:DWORD dst_unused:UNUSED_PAD src0_sel:DWORD src1_sel:WORD_1
	v_lshl_add_u64 v[70:71], v[174:175], 0, v[132:133]
	global_load_dwordx4 v[120:123], v[68:69], off
	global_load_dwordx4 v[116:119], v[70:71], off
	ds_read2_b32 v[204:205], v145 offset0:48 offset1:56
	s_waitcnt lgkmcnt(1)
	v_lshlrev_b32_sdwa v132, v215, v206 dst_sel:DWORD dst_unused:UNUSED_PAD src0_sel:DWORD src1_sel:WORD_1
	v_lshl_add_u64 v[68:69], v[174:175], 0, v[132:133]
	v_lshlrev_b32_sdwa v132, v215, v207 dst_sel:DWORD dst_unused:UNUSED_PAD src0_sel:DWORD src1_sel:WORD_1
	v_lshl_add_u64 v[70:71], v[174:175], 0, v[132:133]
	global_load_dwordx4 v[112:115], v[68:69], off
	global_load_dwordx4 v[108:111], v[70:71], off
	s_waitcnt lgkmcnt(0)
	v_lshlrev_b32_sdwa v132, v215, v204 dst_sel:DWORD dst_unused:UNUSED_PAD src0_sel:DWORD src1_sel:WORD_1
	ds_read2_b32 v[202:203], v145 offset0:64 offset1:72
	v_lshl_add_u64 v[68:69], v[174:175], 0, v[132:133]
	v_lshlrev_b32_sdwa v132, v215, v205 dst_sel:DWORD dst_unused:UNUSED_PAD src0_sel:DWORD src1_sel:WORD_1
	v_lshl_add_u64 v[70:71], v[174:175], 0, v[132:133]
	global_load_dwordx4 v[104:107], v[68:69], off
	global_load_dwordx4 v[100:103], v[70:71], off
	ds_read2_b32 v[200:201], v145 offset0:80 offset1:88
	s_waitcnt lgkmcnt(1)
	v_lshlrev_b32_sdwa v132, v215, v202 dst_sel:DWORD dst_unused:UNUSED_PAD src0_sel:DWORD src1_sel:WORD_1
	v_lshl_add_u64 v[68:69], v[174:175], 0, v[132:133]
	v_lshlrev_b32_sdwa v132, v215, v203 dst_sel:DWORD dst_unused:UNUSED_PAD src0_sel:DWORD src1_sel:WORD_1
	v_lshl_add_u64 v[70:71], v[174:175], 0, v[132:133]
	global_load_dwordx4 v[96:99], v[68:69], off
	global_load_dwordx4 v[92:95], v[70:71], off
	s_waitcnt lgkmcnt(0)
	v_lshlrev_b32_sdwa v132, v215, v200 dst_sel:DWORD dst_unused:UNUSED_PAD src0_sel:DWORD src1_sel:WORD_1
	ds_read2_b32 v[198:199], v145 offset0:96 offset1:104
	v_lshl_add_u64 v[68:69], v[174:175], 0, v[132:133]
	v_lshlrev_b32_sdwa v132, v215, v201 dst_sel:DWORD dst_unused:UNUSED_PAD src0_sel:DWORD src1_sel:WORD_1
	v_lshl_add_u64 v[70:71], v[174:175], 0, v[132:133]
	global_load_dwordx4 v[88:91], v[68:69], off
	global_load_dwordx4 v[84:87], v[70:71], off
	ds_read2_b32 v[196:197], v145 offset0:112 offset1:120
	s_waitcnt lgkmcnt(1)
	v_lshlrev_b32_sdwa v132, v215, v198 dst_sel:DWORD dst_unused:UNUSED_PAD src0_sel:DWORD src1_sel:WORD_1
	v_lshl_add_u64 v[68:69], v[174:175], 0, v[132:133]
	v_lshlrev_b32_sdwa v132, v215, v199 dst_sel:DWORD dst_unused:UNUSED_PAD src0_sel:DWORD src1_sel:WORD_1
	v_lshl_add_u64 v[70:71], v[174:175], 0, v[132:133]
	s_waitcnt lgkmcnt(0)
; DI void up_math(const u32x4 (&W)[16], const u32 (&pj)[16], float* __restrict__ yrow, int lane) {
;     ...
;   for (int j = 0; j < 16; ++j) {
;     const float h = __uint_as_float(pj[j] << 16);
;     const f2 hh = {h, h};
; #pragma unroll
;     for (int d = 0; d < 4; ++d) {
;       f2 lo = __builtin_amdgcn_cvt_pk_f32_fp8((int)W[j][d], false);
;       f2 hi = __builtin_amdgcn_cvt_pk_f32_fp8((int)W[j][d], true);
;       y[2 * d] = lo * hh + y[2 * d];
;       y[2 * d + 1] = hi * hh + y[2 * d + 1];
;     }
;   }
	v_lshlrev_b32_sdwa v132, v215, v196 dst_sel:DWORD dst_unused:UNUSED_PAD src0_sel:DWORD src1_sel:WORD_1
	global_load_dwordx4 v[80:83], v[68:69], off
	global_load_dwordx4 v[76:79], v[70:71], off
	v_lshl_add_u64 v[68:69], v[174:175], 0, v[132:133]
	v_lshlrev_b32_sdwa v132, v215, v197 dst_sel:DWORD dst_unused:UNUSED_PAD src0_sel:DWORD src1_sel:WORD_1
	v_lshl_add_u64 v[70:71], v[174:175], 0, v[132:133]
	global_load_dwordx4 v[72:75], v[68:69], off
	s_nop 0
	global_load_dwordx4 v[68:71], v[70:71], off
	s_waitcnt vmcnt(31)
	v_cvt_pk_f32_fp8_e32 v[216:217], v4
	v_cvt_pk_f32_fp8_sdwa v[226:227], v4 src0_sel:WORD_1
	v_cvt_pk_f32_fp8_e32 v[228:229], v5
	v_cvt_pk_f32_fp8_sdwa v[230:231], v5 src0_sel:WORD_1
	v_cvt_pk_f32_fp8_e32 v[232:233], v6
	v_cvt_pk_f32_fp8_sdwa v[234:235], v6 src0_sel:WORD_1
	v_cvt_pk_f32_fp8_e32 v[236:237], v7
	v_cvt_pk_f32_fp8_sdwa v[238:239], v7 src0_sel:WORD_1
	s_waitcnt vmcnt(30)
	v_cvt_pk_f32_fp8_e32 v[240:241], v8
	v_cvt_pk_f32_fp8_sdwa v[242:243], v8 src0_sel:WORD_1
	v_cvt_pk_f32_fp8_e32 v[244:245], v9
	v_cvt_pk_f32_fp8_sdwa v[246:247], v9 src0_sel:WORD_1
	v_lshlrev_b32_e32 v132, 16, v178
	v_pk_fma_f32 v[216:217], v[132:133], v[216:217], 0 op_sel_hi:[0,1,0]
	v_pk_fma_f32 v[226:227], v[132:133], v[226:227], 0 op_sel_hi:[0,1,0]
	v_pk_fma_f32 v[228:229], v[132:133], v[228:229], 0 op_sel_hi:[0,1,0]
	v_pk_fma_f32 v[230:231], v[132:133], v[230:231], 0 op_sel_hi:[0,1,0]
	v_pk_fma_f32 v[232:233], v[132:133], v[232:233], 0 op_sel_hi:[0,1,0]
	v_pk_fma_f32 v[234:235], v[132:133], v[234:235], 0 op_sel_hi:[0,1,0]
	v_pk_fma_f32 v[236:237], v[132:133], v[236:237], 0 op_sel_hi:[0,1,0]
	v_pk_fma_f32 v[238:239], v[132:133], v[238:239], 0 op_sel_hi:[0,1,0]
	v_lshlrev_b32_e32 v132, 16, v179
	v_pk_fma_f32 v[216:217], v[132:133], v[240:241], v[216:217] op_sel_hi:[0,1,1]
	v_cvt_pk_f32_fp8_e32 v[240:241], v10
	v_pk_fma_f32 v[226:227], v[132:133], v[242:243], v[226:227] op_sel_hi:[0,1,1]
	v_pk_fma_f32 v[228:229], v[132:133], v[244:245], v[228:229] op_sel_hi:[0,1,1]
	v_pk_fma_f32 v[230:231], v[132:133], v[246:247], v[230:231] op_sel_hi:[0,1,1]
	v_cvt_pk_f32_fp8_sdwa v[242:243], v10 src0_sel:WORD_1
	v_cvt_pk_f32_fp8_e32 v[244:245], v11
	v_cvt_pk_f32_fp8_sdwa v[246:247], v11 src0_sel:WORD_1
	v_pk_fma_f32 v[232:233], v[132:133], v[240:241], v[232:233] op_sel_hi:[0,1,1]
	s_waitcnt vmcnt(29)
	v_cvt_pk_f32_fp8_e32 v[240:241], v12
	v_pk_fma_f32 v[234:235], v[132:133], v[242:243], v[234:235] op_sel_hi:[0,1,1]
	v_pk_fma_f32 v[236:237], v[132:133], v[244:245], v[236:237] op_sel_hi:[0,1,1]
	v_pk_fma_f32 v[238:239], v[132:133], v[246:247], v[238:239] op_sel_hi:[0,1,1]
	v_cvt_pk_f32_fp8_sdwa v[242:243], v12 src0_sel:WORD_1
	v_cvt_pk_f32_fp8_e32 v[244:245], v13
	v_cvt_pk_f32_fp8_sdwa v[246:247], v13 src0_sel:WORD_1
	v_lshlrev_b32_e32 v132, 16, v180
	v_pk_fma_f32 v[216:217], v[132:133], v[240:241], v[216:217] op_sel_hi:[0,1,1]
	v_cvt_pk_f32_fp8_e32 v[240:241], v14
	v_pk_fma_f32 v[226:227], v[132:133], v[242:243], v[226:227] op_sel_hi:[0,1,1]
	v_pk_fma_f32 v[228:229], v[132:133], v[244:245], v[228:229] op_sel_hi:[0,1,1]
	v_pk_fma_f32 v[230:231], v[132:133], v[246:247], v[230:231] op_sel_hi:[0,1,1]
	v_cvt_pk_f32_fp8_sdwa v[242:243], v14 src0_sel:WORD_1
	v_cvt_pk_f32_fp8_e32 v[244:245], v15
	v_cvt_pk_f32_fp8_sdwa v[246:247], v15 src0_sel:WORD_1
	v_pk_fma_f32 v[232:233], v[132:133], v[240:241], v[232:233] op_sel_hi:[0,1,1]
	s_waitcnt vmcnt(28)
	v_cvt_pk_f32_fp8_e32 v[240:241], v16
	v_pk_fma_f32 v[234:235], v[132:133], v[242:243], v[234:235] op_sel_hi:[0,1,1]
	v_pk_fma_f32 v[236:237], v[132:133], v[244:245], v[236:237] op_sel_hi:[0,1,1]
	v_pk_fma_f32 v[238:239], v[132:133], v[246:247], v[238:239] op_sel_hi:[0,1,1]
	v_cvt_pk_f32_fp8_sdwa v[242:243], v16 src0_sel:WORD_1
	v_cvt_pk_f32_fp8_e32 v[244:245], v17
	v_cvt_pk_f32_fp8_sdwa v[246:247], v17 src0_sel:WORD_1
	v_lshlrev_b32_e32 v132, 16, v181
	v_pk_fma_f32 v[216:217], v[132:133], v[240:241], v[216:217] op_sel_hi:[0,1,1]
	v_cvt_pk_f32_fp8_e32 v[240:241], v18
	v_pk_fma_f32 v[226:227], v[132:133], v[242:243], v[226:227] op_sel_hi:[0,1,1]
	v_pk_fma_f32 v[228:229], v[132:133], v[244:245], v[228:229] op_sel_hi:[0,1,1]
	v_pk_fma_f32 v[230:231], v[132:133], v[246:247], v[230:231] op_sel_hi:[0,1,1]
	v_cvt_pk_f32_fp8_sdwa v[242:243], v18 src0_sel:WORD_1
	v_cvt_pk_f32_fp8_e32 v[244:245], v19
	v_cvt_pk_f32_fp8_sdwa v[246:247], v19 src0_sel:WORD_1
	v_pk_fma_f32 v[232:233], v[132:133], v[240:241], v[232:233] op_sel_hi:[0,1,1]
	s_waitcnt vmcnt(27)
	v_cvt_pk_f32_fp8_e32 v[240:241], v20
	v_pk_fma_f32 v[234:235], v[132:133], v[242:243], v[234:235] op_sel_hi:[0,1,1]
	v_pk_fma_f32 v[236:237], v[132:133], v[244:245], v[236:237] op_sel_hi:[0,1,1]
	v_pk_fma_f32 v[238:239], v[132:133], v[246:247], v[238:239] op_sel_hi:[0,1,1]
	v_cvt_pk_f32_fp8_sdwa v[242:243], v20 src0_sel:WORD_1
	v_cvt_pk_f32_fp8_e32 v[244:245], v21
	v_cvt_pk_f32_fp8_sdwa v[246:247], v21 src0_sel:WORD_1
	v_lshlrev_b32_e32 v132, 16, v182
	v_pk_fma_f32 v[216:217], v[132:133], v[240:241], v[216:217] op_sel_hi:[0,1,1]
	v_cvt_pk_f32_fp8_e32 v[240:241], v22
	v_pk_fma_f32 v[226:227], v[132:133], v[242:243], v[226:227] op_sel_hi:[0,1,1]
	v_pk_fma_f32 v[228:229], v[132:133], v[244:245], v[228:229] op_sel_hi:[0,1,1]
	v_pk_fma_f32 v[230:231], v[132:133], v[246:247], v[230:231] op_sel_hi:[0,1,1]
	v_cvt_pk_f32_fp8_sdwa v[242:243], v22 src0_sel:WORD_1
	v_cvt_pk_f32_fp8_e32 v[244:245], v23
	v_cvt_pk_f32_fp8_sdwa v[246:247], v23 src0_sel:WORD_1
	v_pk_fma_f32 v[232:233], v[132:133], v[240:241], v[232:233] op_sel_hi:[0,1,1]
	s_waitcnt vmcnt(26)
; DI void up_math(const u32x4 (&W)[16], const u32 (&pj)[16], float* __restrict__ yrow, int lane) {
;     ...
;   for (int j = 0; j < 16; ++j) {
;     const float h = __uint_as_float(pj[j] << 16);
;     const f2 hh = {h, h};
; #pragma unroll
;     for (int d = 0; d < 4; ++d) {
;       f2 lo = __builtin_amdgcn_cvt_pk_f32_fp8((int)W[j][d], false);
;       f2 hi = __builtin_amdgcn_cvt_pk_f32_fp8((int)W[j][d], true);
;       y[2 * d] = lo * hh + y[2 * d];
;       y[2 * d + 1] = hi * hh + y[2 * d + 1];
;     }
;   }
	v_cvt_pk_f32_fp8_e32 v[240:241], v24
	v_pk_fma_f32 v[234:235], v[132:133], v[242:243], v[234:235] op_sel_hi:[0,1,1]
	v_pk_fma_f32 v[236:237], v[132:133], v[244:245], v[236:237] op_sel_hi:[0,1,1]
	v_pk_fma_f32 v[238:239], v[132:133], v[246:247], v[238:239] op_sel_hi:[0,1,1]
	v_cvt_pk_f32_fp8_sdwa v[242:243], v24 src0_sel:WORD_1
	v_cvt_pk_f32_fp8_e32 v[244:245], v25
	v_cvt_pk_f32_fp8_sdwa v[246:247], v25 src0_sel:WORD_1
	v_lshlrev_b32_e32 v132, 16, v183
	v_pk_fma_f32 v[216:217], v[132:133], v[240:241], v[216:217] op_sel_hi:[0,1,1]
	v_cvt_pk_f32_fp8_e32 v[240:241], v26
	v_pk_fma_f32 v[226:227], v[132:133], v[242:243], v[226:227] op_sel_hi:[0,1,1]
	v_pk_fma_f32 v[228:229], v[132:133], v[244:245], v[228:229] op_sel_hi:[0,1,1]
	v_pk_fma_f32 v[230:231], v[132:133], v[246:247], v[230:231] op_sel_hi:[0,1,1]
	v_cvt_pk_f32_fp8_sdwa v[242:243], v26 src0_sel:WORD_1
	v_cvt_pk_f32_fp8_e32 v[244:245], v27
	v_cvt_pk_f32_fp8_sdwa v[246:247], v27 src0_sel:WORD_1
	v_pk_fma_f32 v[232:233], v[132:133], v[240:241], v[232:233] op_sel_hi:[0,1,1]
	s_waitcnt vmcnt(25)
	v_cvt_pk_f32_fp8_e32 v[240:241], v28
	v_pk_fma_f32 v[234:235], v[132:133], v[242:243], v[234:235] op_sel_hi:[0,1,1]
	v_pk_fma_f32 v[236:237], v[132:133], v[244:245], v[236:237] op_sel_hi:[0,1,1]
	v_pk_fma_f32 v[238:239], v[132:133], v[246:247], v[238:239] op_sel_hi:[0,1,1]
	v_cvt_pk_f32_fp8_sdwa v[242:243], v28 src0_sel:WORD_1
	v_cvt_pk_f32_fp8_e32 v[244:245], v29
	v_cvt_pk_f32_fp8_sdwa v[246:247], v29 src0_sel:WORD_1
	v_lshlrev_b32_e32 v132, 16, v184
	v_pk_fma_f32 v[216:217], v[132:133], v[240:241], v[216:217] op_sel_hi:[0,1,1]
	v_cvt_pk_f32_fp8_e32 v[240:241], v30
	v_pk_fma_f32 v[226:227], v[132:133], v[242:243], v[226:227] op_sel_hi:[0,1,1]
	v_pk_fma_f32 v[228:229], v[132:133], v[244:245], v[228:229] op_sel_hi:[0,1,1]
	v_pk_fma_f32 v[230:231], v[132:133], v[246:247], v[230:231] op_sel_hi:[0,1,1]
	v_cvt_pk_f32_fp8_sdwa v[242:243], v30 src0_sel:WORD_1
	v_cvt_pk_f32_fp8_e32 v[244:245], v31
	v_cvt_pk_f32_fp8_sdwa v[246:247], v31 src0_sel:WORD_1
	v_pk_fma_f32 v[232:233], v[132:133], v[240:241], v[232:233] op_sel_hi:[0,1,1]
	s_waitcnt vmcnt(24)
	v_cvt_pk_f32_fp8_e32 v[240:241], v32
	v_pk_fma_f32 v[234:235], v[132:133], v[242:243], v[234:235] op_sel_hi:[0,1,1]
	v_pk_fma_f32 v[236:237], v[132:133], v[244:245], v[236:237] op_sel_hi:[0,1,1]
	v_pk_fma_f32 v[238:239], v[132:133], v[246:247], v[238:239] op_sel_hi:[0,1,1]
	v_cvt_pk_f32_fp8_sdwa v[242:243], v32 src0_sel:WORD_1
	v_cvt_pk_f32_fp8_e32 v[244:245], v33
	v_cvt_pk_f32_fp8_sdwa v[246:247], v33 src0_sel:WORD_1
	v_lshlrev_b32_e32 v132, 16, v185
	v_pk_fma_f32 v[216:217], v[132:133], v[240:241], v[216:217] op_sel_hi:[0,1,1]
	v_cvt_pk_f32_fp8_e32 v[240:241], v34
	v_pk_fma_f32 v[226:227], v[132:133], v[242:243], v[226:227] op_sel_hi:[0,1,1]
	v_pk_fma_f32 v[228:229], v[132:133], v[244:245], v[228:229] op_sel_hi:[0,1,1]
	v_pk_fma_f32 v[230:231], v[132:133], v[246:247], v[230:231] op_sel_hi:[0,1,1]
	v_cvt_pk_f32_fp8_sdwa v[242:243], v34 src0_sel:WORD_1
	v_cvt_pk_f32_fp8_e32 v[244:245], v35
	v_cvt_pk_f32_fp8_sdwa v[246:247], v35 src0_sel:WORD_1
	v_pk_fma_f32 v[232:233], v[132:133], v[240:241], v[232:233] op_sel_hi:[0,1,1]
	s_waitcnt vmcnt(23)
	v_cvt_pk_f32_fp8_e32 v[240:241], v36
	v_pk_fma_f32 v[234:235], v[132:133], v[242:243], v[234:235] op_sel_hi:[0,1,1]
	v_pk_fma_f32 v[236:237], v[132:133], v[244:245], v[236:237] op_sel_hi:[0,1,1]
	v_pk_fma_f32 v[238:239], v[132:133], v[246:247], v[238:239] op_sel_hi:[0,1,1]
	v_cvt_pk_f32_fp8_sdwa v[242:243], v36 src0_sel:WORD_1
	v_cvt_pk_f32_fp8_e32 v[244:245], v37
	v_cvt_pk_f32_fp8_sdwa v[246:247], v37 src0_sel:WORD_1
	v_lshlrev_b32_e32 v132, 16, v186
	v_pk_fma_f32 v[216:217], v[132:133], v[240:241], v[216:217] op_sel_hi:[0,1,1]
	v_cvt_pk_f32_fp8_e32 v[240:241], v38
	v_pk_fma_f32 v[226:227], v[132:133], v[242:243], v[226:227] op_sel_hi:[0,1,1]
	v_pk_fma_f32 v[228:229], v[132:133], v[244:245], v[228:229] op_sel_hi:[0,1,1]
	v_pk_fma_f32 v[230:231], v[132:133], v[246:247], v[230:231] op_sel_hi:[0,1,1]
	v_cvt_pk_f32_fp8_sdwa v[242:243], v38 src0_sel:WORD_1
	v_cvt_pk_f32_fp8_e32 v[244:245], v39
	v_cvt_pk_f32_fp8_sdwa v[246:247], v39 src0_sel:WORD_1
	v_pk_fma_f32 v[232:233], v[132:133], v[240:241], v[232:233] op_sel_hi:[0,1,1]
	s_waitcnt vmcnt(22)
	v_cvt_pk_f32_fp8_e32 v[240:241], v40
	v_pk_fma_f32 v[234:235], v[132:133], v[242:243], v[234:235] op_sel_hi:[0,1,1]
	v_pk_fma_f32 v[236:237], v[132:133], v[244:245], v[236:237] op_sel_hi:[0,1,1]
	v_pk_fma_f32 v[238:239], v[132:133], v[246:247], v[238:239] op_sel_hi:[0,1,1]
	v_cvt_pk_f32_fp8_sdwa v[242:243], v40 src0_sel:WORD_1
	v_cvt_pk_f32_fp8_e32 v[244:245], v41
	v_cvt_pk_f32_fp8_sdwa v[246:247], v41 src0_sel:WORD_1
	v_lshlrev_b32_e32 v132, 16, v187
	v_pk_fma_f32 v[216:217], v[132:133], v[240:241], v[216:217] op_sel_hi:[0,1,1]
	v_cvt_pk_f32_fp8_e32 v[240:241], v42
	v_pk_fma_f32 v[226:227], v[132:133], v[242:243], v[226:227] op_sel_hi:[0,1,1]
	v_pk_fma_f32 v[228:229], v[132:133], v[244:245], v[228:229] op_sel_hi:[0,1,1]
	v_pk_fma_f32 v[230:231], v[132:133], v[246:247], v[230:231] op_sel_hi:[0,1,1]
	v_cvt_pk_f32_fp8_sdwa v[242:243], v42 src0_sel:WORD_1
	v_cvt_pk_f32_fp8_e32 v[244:245], v43
	v_cvt_pk_f32_fp8_sdwa v[246:247], v43 src0_sel:WORD_1
	v_pk_fma_f32 v[232:233], v[132:133], v[240:241], v[232:233] op_sel_hi:[0,1,1]
	s_waitcnt vmcnt(21)
; DI void up_math(const u32x4 (&W)[16], const u32 (&pj)[16], float* __restrict__ yrow, int lane) {
;     ...
;   for (int j = 0; j < 16; ++j) {
;     const float h = __uint_as_float(pj[j] << 16);
;     const f2 hh = {h, h};
; #pragma unroll
;     for (int d = 0; d < 4; ++d) {
;       f2 lo = __builtin_amdgcn_cvt_pk_f32_fp8((int)W[j][d], false);
;       f2 hi = __builtin_amdgcn_cvt_pk_f32_fp8((int)W[j][d], true);
;       y[2 * d] = lo * hh + y[2 * d];
;       y[2 * d + 1] = hi * hh + y[2 * d + 1];
;     }
;   }
	v_cvt_pk_f32_fp8_e32 v[240:241], v44
	v_pk_fma_f32 v[234:235], v[132:133], v[242:243], v[234:235] op_sel_hi:[0,1,1]
	v_pk_fma_f32 v[236:237], v[132:133], v[244:245], v[236:237] op_sel_hi:[0,1,1]
	v_pk_fma_f32 v[238:239], v[132:133], v[246:247], v[238:239] op_sel_hi:[0,1,1]
	v_cvt_pk_f32_fp8_sdwa v[242:243], v44 src0_sel:WORD_1
	v_cvt_pk_f32_fp8_e32 v[244:245], v45
	v_cvt_pk_f32_fp8_sdwa v[246:247], v45 src0_sel:WORD_1
	v_lshlrev_b32_e32 v132, 16, v190
	v_pk_fma_f32 v[216:217], v[132:133], v[240:241], v[216:217] op_sel_hi:[0,1,1]
	v_cvt_pk_f32_fp8_e32 v[240:241], v46
	v_pk_fma_f32 v[226:227], v[132:133], v[242:243], v[226:227] op_sel_hi:[0,1,1]
	v_pk_fma_f32 v[228:229], v[132:133], v[244:245], v[228:229] op_sel_hi:[0,1,1]
	v_pk_fma_f32 v[230:231], v[132:133], v[246:247], v[230:231] op_sel_hi:[0,1,1]
	v_cvt_pk_f32_fp8_sdwa v[242:243], v46 src0_sel:WORD_1
	v_cvt_pk_f32_fp8_e32 v[244:245], v47
	v_cvt_pk_f32_fp8_sdwa v[246:247], v47 src0_sel:WORD_1
	v_pk_fma_f32 v[232:233], v[132:133], v[240:241], v[232:233] op_sel_hi:[0,1,1]
	s_waitcnt vmcnt(20)
	v_cvt_pk_f32_fp8_e32 v[240:241], v48
	v_pk_fma_f32 v[234:235], v[132:133], v[242:243], v[234:235] op_sel_hi:[0,1,1]
	v_pk_fma_f32 v[236:237], v[132:133], v[244:245], v[236:237] op_sel_hi:[0,1,1]
	v_pk_fma_f32 v[238:239], v[132:133], v[246:247], v[238:239] op_sel_hi:[0,1,1]
	v_cvt_pk_f32_fp8_sdwa v[242:243], v48 src0_sel:WORD_1
	v_cvt_pk_f32_fp8_e32 v[244:245], v49
	v_cvt_pk_f32_fp8_sdwa v[246:247], v49 src0_sel:WORD_1
	v_lshlrev_b32_e32 v132, 16, v191
	v_pk_fma_f32 v[216:217], v[132:133], v[240:241], v[216:217] op_sel_hi:[0,1,1]
	v_cvt_pk_f32_fp8_e32 v[240:241], v50
	v_pk_fma_f32 v[226:227], v[132:133], v[242:243], v[226:227] op_sel_hi:[0,1,1]
	v_pk_fma_f32 v[228:229], v[132:133], v[244:245], v[228:229] op_sel_hi:[0,1,1]
	v_pk_fma_f32 v[230:231], v[132:133], v[246:247], v[230:231] op_sel_hi:[0,1,1]
	v_cvt_pk_f32_fp8_sdwa v[242:243], v50 src0_sel:WORD_1
	v_cvt_pk_f32_fp8_e32 v[244:245], v51
	v_cvt_pk_f32_fp8_sdwa v[246:247], v51 src0_sel:WORD_1
	v_pk_fma_f32 v[232:233], v[132:133], v[240:241], v[232:233] op_sel_hi:[0,1,1]
	s_waitcnt vmcnt(19)
	v_cvt_pk_f32_fp8_e32 v[240:241], v52
	v_pk_fma_f32 v[234:235], v[132:133], v[242:243], v[234:235] op_sel_hi:[0,1,1]
	v_pk_fma_f32 v[236:237], v[132:133], v[244:245], v[236:237] op_sel_hi:[0,1,1]
	v_pk_fma_f32 v[238:239], v[132:133], v[246:247], v[238:239] op_sel_hi:[0,1,1]
	v_cvt_pk_f32_fp8_sdwa v[242:243], v52 src0_sel:WORD_1
	v_cvt_pk_f32_fp8_e32 v[244:245], v53
	v_cvt_pk_f32_fp8_sdwa v[246:247], v53 src0_sel:WORD_1
	v_lshlrev_b32_e32 v132, 16, v192
	v_pk_fma_f32 v[216:217], v[132:133], v[240:241], v[216:217] op_sel_hi:[0,1,1]
	v_cvt_pk_f32_fp8_e32 v[240:241], v54
	v_pk_fma_f32 v[226:227], v[132:133], v[242:243], v[226:227] op_sel_hi:[0,1,1]
	v_pk_fma_f32 v[228:229], v[132:133], v[244:245], v[228:229] op_sel_hi:[0,1,1]
	v_pk_fma_f32 v[230:231], v[132:133], v[246:247], v[230:231] op_sel_hi:[0,1,1]
	v_cvt_pk_f32_fp8_sdwa v[242:243], v54 src0_sel:WORD_1
	v_cvt_pk_f32_fp8_e32 v[244:245], v55
	v_cvt_pk_f32_fp8_sdwa v[246:247], v55 src0_sel:WORD_1
	v_pk_fma_f32 v[232:233], v[132:133], v[240:241], v[232:233] op_sel_hi:[0,1,1]
	s_waitcnt vmcnt(18)
	v_cvt_pk_f32_fp8_e32 v[240:241], v56
	v_pk_fma_f32 v[234:235], v[132:133], v[242:243], v[234:235] op_sel_hi:[0,1,1]
	v_pk_fma_f32 v[236:237], v[132:133], v[244:245], v[236:237] op_sel_hi:[0,1,1]
	v_pk_fma_f32 v[238:239], v[132:133], v[246:247], v[238:239] op_sel_hi:[0,1,1]
	v_cvt_pk_f32_fp8_sdwa v[242:243], v56 src0_sel:WORD_1
	v_cvt_pk_f32_fp8_e32 v[244:245], v57
	v_cvt_pk_f32_fp8_sdwa v[246:247], v57 src0_sel:WORD_1
	v_lshlrev_b32_e32 v132, 16, v193
	v_pk_fma_f32 v[216:217], v[132:133], v[240:241], v[216:217] op_sel_hi:[0,1,1]
	v_cvt_pk_f32_fp8_e32 v[240:241], v58
	v_pk_fma_f32 v[226:227], v[132:133], v[242:243], v[226:227] op_sel_hi:[0,1,1]
	v_pk_fma_f32 v[228:229], v[132:133], v[244:245], v[228:229] op_sel_hi:[0,1,1]
	v_pk_fma_f32 v[230:231], v[132:133], v[246:247], v[230:231] op_sel_hi:[0,1,1]
	v_cvt_pk_f32_fp8_sdwa v[242:243], v58 src0_sel:WORD_1
	v_cvt_pk_f32_fp8_e32 v[244:245], v59
	v_cvt_pk_f32_fp8_sdwa v[246:247], v59 src0_sel:WORD_1
	v_pk_fma_f32 v[232:233], v[132:133], v[240:241], v[232:233] op_sel_hi:[0,1,1]
	s_waitcnt vmcnt(17)
	v_cvt_pk_f32_fp8_e32 v[240:241], v60
	v_pk_fma_f32 v[234:235], v[132:133], v[242:243], v[234:235] op_sel_hi:[0,1,1]
	v_pk_fma_f32 v[236:237], v[132:133], v[244:245], v[236:237] op_sel_hi:[0,1,1]
	v_pk_fma_f32 v[238:239], v[132:133], v[246:247], v[238:239] op_sel_hi:[0,1,1]
	v_cvt_pk_f32_fp8_sdwa v[242:243], v60 src0_sel:WORD_1
	v_cvt_pk_f32_fp8_e32 v[244:245], v61
	v_cvt_pk_f32_fp8_sdwa v[246:247], v61 src0_sel:WORD_1
	v_lshlrev_b32_e32 v132, 16, v194
	v_pk_fma_f32 v[216:217], v[132:133], v[240:241], v[216:217] op_sel_hi:[0,1,1]
	v_cvt_pk_f32_fp8_e32 v[240:241], v62
	v_pk_fma_f32 v[226:227], v[132:133], v[242:243], v[226:227] op_sel_hi:[0,1,1]
	v_pk_fma_f32 v[228:229], v[132:133], v[244:245], v[228:229] op_sel_hi:[0,1,1]
	v_pk_fma_f32 v[230:231], v[132:133], v[246:247], v[230:231] op_sel_hi:[0,1,1]
	v_cvt_pk_f32_fp8_sdwa v[242:243], v62 src0_sel:WORD_1
	v_cvt_pk_f32_fp8_e32 v[244:245], v63
	v_cvt_pk_f32_fp8_sdwa v[246:247], v63 src0_sel:WORD_1
	v_pk_fma_f32 v[232:233], v[132:133], v[240:241], v[232:233] op_sel_hi:[0,1,1]
	s_waitcnt vmcnt(16)
; DI void up_issue(u32x4 (&W)[16], u32 (&pj)[16], const u32* pl, const unsigned char* wbase, int grp) {
; #pragma unroll
;   for (int j = 0; j < 16; ++j) {
;     pj[j] = pl[8 * j + grp];
;     W[j] = *(const u32x4*)(wbase + (size_t)(pj[j] >> 16) * 1024);
;   }
; DI void up_math(const u32x4 (&W)[16], const u32 (&pj)[16], float* __restrict__ yrow, int lane) {
;     ...
;   const bool b5 = lane & 32, b4 = lane & 16, b3 = lane & 8;
;   f2 q4[4];
; #pragma unroll
;   for (int i = 0; i < 4; ++i) {
;     f2 snd = b5 ? y[i] : y[i + 4]; f2 kp = b5 ? y[i + 4] : y[i];
;     q4[i] = f2{kp.x + __shfl_xor(snd.x, 32), kp.y + __shfl_xor(snd.y, 32)};
;   }
;   f2 r2[2];
; #pragma unroll
;   for (int i = 0; i < 2; ++i) {
;     f2 snd = b4 ? q4[i] : q4[i + 2]; f2 kp = b4 ? q4[i + 2] : q4[i];
;     r2[i] = f2{kp.x + __shfl_xor(snd.x, 16), kp.y + __shfl_xor(snd.y, 16)};
;   }
;   f2 a;
;   { f2 snd = b3 ? r2[0] : r2[1]; f2 kp = b3 ? r2[1] : r2[0]; a = f2{kp.x + __shfl_xor(snd.x, 8), kp.y + __shfl_xor(snd.y, 8)}; }
;   const int ci = (b5 ? 4 : 0) + (b4 ? 2 : 0) + (b3 ? 1 : 0);
;   *(float2*)(yrow + (lane & 7) * 16 + 2 * ci) = make_float2(a.x, a.y);
	v_cvt_pk_f32_fp8_e32 v[240:241], v64
	v_pk_fma_f32 v[234:235], v[132:133], v[242:243], v[234:235] op_sel_hi:[0,1,1]
	v_pk_fma_f32 v[236:237], v[132:133], v[244:245], v[236:237] op_sel_hi:[0,1,1]
	v_pk_fma_f32 v[238:239], v[132:133], v[246:247], v[238:239] op_sel_hi:[0,1,1]
	v_cvt_pk_f32_fp8_sdwa v[242:243], v64 src0_sel:WORD_1
	v_cvt_pk_f32_fp8_e32 v[244:245], v65
	v_cvt_pk_f32_fp8_sdwa v[246:247], v65 src0_sel:WORD_1
	v_lshlrev_b32_e32 v132, 16, v195
	v_pk_fma_f32 v[216:217], v[132:133], v[240:241], v[216:217] op_sel_hi:[0,1,1]
	v_cvt_pk_f32_fp8_e32 v[240:241], v66
	v_pk_fma_f32 v[226:227], v[132:133], v[242:243], v[226:227] op_sel_hi:[0,1,1]
	v_pk_fma_f32 v[228:229], v[132:133], v[244:245], v[228:229] op_sel_hi:[0,1,1]
	v_pk_fma_f32 v[230:231], v[132:133], v[246:247], v[230:231] op_sel_hi:[0,1,1]
	v_cvt_pk_f32_fp8_sdwa v[242:243], v66 src0_sel:WORD_1
	v_cvt_pk_f32_fp8_e32 v[244:245], v67
	v_cvt_pk_f32_fp8_sdwa v[246:247], v67 src0_sel:WORD_1
	v_pk_fma_f32 v[232:233], v[132:133], v[240:241], v[232:233] op_sel_hi:[0,1,1]
	v_pk_fma_f32 v[234:235], v[132:133], v[242:243], v[234:235] op_sel_hi:[0,1,1]
	v_pk_fma_f32 v[236:237], v[132:133], v[244:245], v[236:237] op_sel_hi:[0,1,1]
	v_pk_fma_f32 v[238:239], v[132:133], v[246:247], v[238:239] op_sel_hi:[0,1,1]
	s_nop 1
	v_permlane32_swap_b32_e32 v216, v232
	v_permlane32_swap_b32_e32 v217, v233
	v_permlane32_swap_b32_e32 v228, v236
	v_permlane32_swap_b32_e32 v229, v237
	v_permlane32_swap_b32_e32 v226, v234
	v_permlane32_swap_b32_e32 v227, v235
	v_permlane32_swap_b32_e32 v230, v238
	v_permlane32_swap_b32_e32 v231, v239
	v_pk_add_f32 v[216:217], v[216:217], v[232:233]
	v_pk_add_f32 v[228:229], v[228:229], v[236:237]
	v_pk_add_f32 v[226:227], v[226:227], v[234:235]
	v_pk_add_f32 v[230:231], v[230:231], v[238:239]
	s_nop 1
	v_permlane16_swap_b32_e32 v216, v228
	v_permlane16_swap_b32_e32 v217, v229
	v_permlane16_swap_b32_e32 v226, v230
	v_permlane16_swap_b32_e32 v227, v231
	v_pk_add_f32 v[216:217], v[216:217], v[228:229]
	v_pk_add_f32 v[226:227], v[226:227], v[230:231]
	s_nop 1
	v_add_f32_dpp v216, v216, v216 row_shl:8 row_mask:0xf bank_mask:0x3
	v_add_f32_dpp v217, v217, v217 row_shl:8 row_mask:0xf bank_mask:0x3
	v_add_f32_dpp v216, v226, v226 row_shr:8 row_mask:0xf bank_mask:0xc
	v_add_f32_dpp v217, v227, v227 row_shr:8 row_mask:0xf bank_mask:0xc
	global_store_dwordx2 v[188:189], v[216:217], off
	s_cmp_gt_u32 s44, 13
	s_cselect_b64 s[28:29], -1, 0
	s_and_b64 vcc, exec, s[28:29]
	s_cbranch_vccnz .LBB0_826
	ds_read2_b32 v[178:179], v145 offset0:128 offset1:136
	ds_read2_b32 v[180:181], v145 offset0:144 offset1:152
	s_waitcnt lgkmcnt(1)
	v_lshlrev_b32_sdwa v132, v215, v178 dst_sel:DWORD dst_unused:UNUSED_PAD src0_sel:DWORD src1_sel:WORD_1
	v_lshl_add_u64 v[4:5], v[174:175], 0, v[132:133]
	v_lshlrev_b32_sdwa v132, v215, v179 dst_sel:DWORD dst_unused:UNUSED_PAD src0_sel:DWORD src1_sel:WORD_1
	v_lshl_add_u64 v[8:9], v[174:175], 0, v[132:133]
	s_waitcnt lgkmcnt(0)
	v_lshlrev_b32_sdwa v132, v215, v180 dst_sel:DWORD dst_unused:UNUSED_PAD src0_sel:DWORD src1_sel:WORD_1
	global_load_dwordx4 v[4:7], v[4:5], off
	s_nop 0
	global_load_dwordx4 v[8:11], v[8:9], off
	v_lshl_add_u64 v[12:13], v[174:175], 0, v[132:133]
	ds_read2_b32 v[182:183], v145 offset0:160 offset1:168
	v_lshlrev_b32_sdwa v132, v215, v181 dst_sel:DWORD dst_unused:UNUSED_PAD src0_sel:DWORD src1_sel:WORD_1
	v_lshl_add_u64 v[16:17], v[174:175], 0, v[132:133]
	global_load_dwordx4 v[12:15], v[12:13], off
	s_nop 0
	global_load_dwordx4 v[16:19], v[16:17], off
	ds_read2_b32 v[184:185], v145 offset0:176 offset1:184
	s_waitcnt lgkmcnt(1)
	v_lshlrev_b32_sdwa v132, v215, v182 dst_sel:DWORD dst_unused:UNUSED_PAD src0_sel:DWORD src1_sel:WORD_1
	v_lshl_add_u64 v[20:21], v[174:175], 0, v[132:133]
	v_lshlrev_b32_sdwa v132, v215, v183 dst_sel:DWORD dst_unused:UNUSED_PAD src0_sel:DWORD src1_sel:WORD_1
	v_lshl_add_u64 v[24:25], v[174:175], 0, v[132:133]
	s_waitcnt lgkmcnt(0)
	v_lshlrev_b32_sdwa v132, v215, v184 dst_sel:DWORD dst_unused:UNUSED_PAD src0_sel:DWORD src1_sel:WORD_1
	global_load_dwordx4 v[20:23], v[20:21], off
	s_nop 0
	global_load_dwordx4 v[24:27], v[24:25], off
	v_lshl_add_u64 v[28:29], v[174:175], 0, v[132:133]
	ds_read2_b32 v[186:187], v145 offset0:192 offset1:200
	v_lshlrev_b32_sdwa v132, v215, v185 dst_sel:DWORD dst_unused:UNUSED_PAD src0_sel:DWORD src1_sel:WORD_1
	v_lshl_add_u64 v[32:33], v[174:175], 0, v[132:133]
	global_load_dwordx4 v[28:31], v[28:29], off
	s_nop 0
	global_load_dwordx4 v[32:35], v[32:33], off
	ds_read2_b32 v[190:191], v145 offset0:208 offset1:216
	s_waitcnt lgkmcnt(1)
	v_lshlrev_b32_sdwa v132, v215, v186 dst_sel:DWORD dst_unused:UNUSED_PAD src0_sel:DWORD src1_sel:WORD_1
	v_lshl_add_u64 v[36:37], v[174:175], 0, v[132:133]
	v_lshlrev_b32_sdwa v132, v215, v187 dst_sel:DWORD dst_unused:UNUSED_PAD src0_sel:DWORD src1_sel:WORD_1
	v_lshl_add_u64 v[40:41], v[174:175], 0, v[132:133]
	s_waitcnt lgkmcnt(0)
	v_lshlrev_b32_sdwa v132, v215, v190 dst_sel:DWORD dst_unused:UNUSED_PAD src0_sel:DWORD src1_sel:WORD_1
	global_load_dwordx4 v[36:39], v[36:37], off
	s_nop 0
	global_load_dwordx4 v[40:43], v[40:41], off
	v_lshl_add_u64 v[44:45], v[174:175], 0, v[132:133]
	ds_read2_b32 v[192:193], v145 offset0:224 offset1:232
	v_lshlrev_b32_sdwa v132, v215, v191 dst_sel:DWORD dst_unused:UNUSED_PAD src0_sel:DWORD src1_sel:WORD_1
	v_lshl_add_u64 v[48:49], v[174:175], 0, v[132:133]
	global_load_dwordx4 v[44:47], v[44:45], off
	s_nop 0
	global_load_dwordx4 v[48:51], v[48:49], off
	ds_read2_b32 v[194:195], v145 offset0:240 offset1:248
	s_waitcnt lgkmcnt(1)
	v_lshlrev_b32_sdwa v132, v215, v192 dst_sel:DWORD dst_unused:UNUSED_PAD src0_sel:DWORD src1_sel:WORD_1
	v_lshl_add_u64 v[52:53], v[174:175], 0, v[132:133]
	v_lshlrev_b32_sdwa v132, v215, v193 dst_sel:DWORD dst_unused:UNUSED_PAD src0_sel:DWORD src1_sel:WORD_1
	v_lshl_add_u64 v[56:57], v[174:175], 0, v[132:133]
	s_waitcnt lgkmcnt(0)
	v_lshlrev_b32_sdwa v132, v215, v194 dst_sel:DWORD dst_unused:UNUSED_PAD src0_sel:DWORD src1_sel:WORD_1
	v_lshl_add_u64 v[60:61], v[174:175], 0, v[132:133]
	v_lshlrev_b32_sdwa v132, v215, v195 dst_sel:DWORD dst_unused:UNUSED_PAD src0_sel:DWORD src1_sel:WORD_1
	v_lshl_add_u64 v[64:65], v[174:175], 0, v[132:133]
	global_load_dwordx4 v[52:55], v[52:53], off
	s_nop 0
	global_load_dwordx4 v[56:59], v[56:57], off
	s_nop 0
	global_load_dwordx4 v[60:63], v[60:61], off
	s_nop 0
	global_load_dwordx4 v[64:67], v[64:65], off
	s_branch .LBB0_826

; DI void up_math(const u32x4 (&W)[16], const u32 (&pj)[16], float* __restrict__ yrow, int lane) {
;     ...
;   for (int j = 0; j < 16; ++j) {
;     const float h = __uint_as_float(pj[j] << 16);
;     const f2 hh = {h, h};
; #pragma unroll
;     for (int d = 0; d < 4; ++d) {
;       f2 lo = __builtin_amdgcn_cvt_pk_f32_fp8((int)W[j][d], false);
;       f2 hi = __builtin_amdgcn_cvt_pk_f32_fp8((int)W[j][d], true);
;       y[2 * d] = lo * hh + y[2 * d];
;       y[2 * d + 1] = hi * hh + y[2 * d + 1];
;     }
;   }
.LBB0_1649:
	s_add_i32 s36, s36, 2
	s_waitcnt vmcnt(16)
	v_cvt_pk_f32_fp8_e32 v[216:217], v128
	v_cvt_pk_f32_fp8_sdwa v[226:227], v128 src0_sel:WORD_1
	v_cvt_pk_f32_fp8_e32 v[228:229], v129
	v_cvt_pk_f32_fp8_sdwa v[128:129], v129 src0_sel:WORD_1
	v_cvt_pk_f32_fp8_e32 v[230:231], v130
	v_cvt_pk_f32_fp8_sdwa v[232:233], v130 src0_sel:WORD_1
	v_cvt_pk_f32_fp8_e32 v[234:235], v131
	v_cvt_pk_f32_fp8_sdwa v[130:131], v131 src0_sel:WORD_1
	v_lshlrev_b32_e32 v132, 16, v210
	v_pk_fma_f32 v[216:217], v[132:133], v[216:217], 0 op_sel_hi:[0,1,0]
	v_pk_fma_f32 v[226:227], v[132:133], v[226:227], 0 op_sel_hi:[0,1,0]
	v_pk_fma_f32 v[228:229], v[132:133], v[228:229], 0 op_sel_hi:[0,1,0]
	v_pk_fma_f32 v[128:129], v[132:133], v[128:129], 0 op_sel_hi:[0,1,0]
	v_pk_fma_f32 v[230:231], v[132:133], v[230:231], 0 op_sel_hi:[0,1,0]
	v_pk_fma_f32 v[232:233], v[132:133], v[232:233], 0 op_sel_hi:[0,1,0]
	v_pk_fma_f32 v[234:235], v[132:133], v[234:235], 0 op_sel_hi:[0,1,0]
	v_pk_fma_f32 v[130:131], v[132:133], v[130:131], 0 op_sel_hi:[0,1,0]
	v_lshlrev_b32_e32 v132, 16, v211
	s_waitcnt vmcnt(15)
	v_cvt_pk_f32_fp8_e32 v[210:211], v124
	v_cvt_pk_f32_fp8_sdwa v[236:237], v124 src0_sel:WORD_1
	v_cvt_pk_f32_fp8_e32 v[238:239], v125
	v_cvt_pk_f32_fp8_sdwa v[124:125], v125 src0_sel:WORD_1
	v_pk_fma_f32 v[210:211], v[132:133], v[210:211], v[216:217] op_sel_hi:[0,1,1]
	v_pk_fma_f32 v[216:217], v[132:133], v[236:237], v[226:227] op_sel_hi:[0,1,1]
	v_pk_fma_f32 v[226:227], v[132:133], v[238:239], v[228:229] op_sel_hi:[0,1,1]
	v_pk_fma_f32 v[124:125], v[132:133], v[124:125], v[128:129] op_sel_hi:[0,1,1]
	v_cvt_pk_f32_fp8_e32 v[128:129], v126
	v_cvt_pk_f32_fp8_sdwa v[228:229], v126 src0_sel:WORD_1
	v_cvt_pk_f32_fp8_e32 v[236:237], v127
	v_cvt_pk_f32_fp8_sdwa v[126:127], v127 src0_sel:WORD_1
	v_pk_fma_f32 v[128:129], v[132:133], v[128:129], v[230:231] op_sel_hi:[0,1,1]
	v_pk_fma_f32 v[228:229], v[132:133], v[228:229], v[232:233] op_sel_hi:[0,1,1]
	v_pk_fma_f32 v[230:231], v[132:133], v[236:237], v[234:235] op_sel_hi:[0,1,1]
	s_waitcnt vmcnt(14)
	v_cvt_pk_f32_fp8_e32 v[232:233], v120
	v_cvt_pk_f32_fp8_sdwa v[234:235], v120 src0_sel:WORD_1
	v_cvt_pk_f32_fp8_e32 v[236:237], v121
	v_cvt_pk_f32_fp8_sdwa v[120:121], v121 src0_sel:WORD_1
	v_pk_fma_f32 v[126:127], v[132:133], v[126:127], v[130:131] op_sel_hi:[0,1,1]
	v_lshlrev_b32_e32 v130, 16, v208
	v_pk_fma_f32 v[210:211], v[130:131], v[232:233], v[210:211] op_sel_hi:[0,1,1]
	v_pk_fma_f32 v[216:217], v[130:131], v[234:235], v[216:217] op_sel_hi:[0,1,1]
	v_pk_fma_f32 v[120:121], v[130:131], v[120:121], v[124:125] op_sel_hi:[0,1,1]
	v_cvt_pk_f32_fp8_e32 v[124:125], v122
	v_cvt_pk_f32_fp8_sdwa v[232:233], v122 src0_sel:WORD_1
	v_cvt_pk_f32_fp8_e32 v[234:235], v123
	v_cvt_pk_f32_fp8_sdwa v[122:123], v123 src0_sel:WORD_1
	v_pk_fma_f32 v[226:227], v[130:131], v[236:237], v[226:227] op_sel_hi:[0,1,1]
	v_pk_fma_f32 v[124:125], v[130:131], v[124:125], v[128:129] op_sel_hi:[0,1,1]
	v_pk_fma_f32 v[128:129], v[130:131], v[232:233], v[228:229] op_sel_hi:[0,1,1]
	v_pk_fma_f32 v[228:229], v[130:131], v[234:235], v[230:231] op_sel_hi:[0,1,1]
	v_pk_fma_f32 v[122:123], v[130:131], v[122:123], v[126:127] op_sel_hi:[0,1,1]
	v_lshlrev_b32_e32 v126, 16, v209
	s_waitcnt vmcnt(13)
	v_cvt_pk_f32_fp8_e32 v[130:131], v116
	v_cvt_pk_f32_fp8_sdwa v[208:209], v116 src0_sel:WORD_1
	v_cvt_pk_f32_fp8_e32 v[230:231], v117
	v_cvt_pk_f32_fp8_sdwa v[116:117], v117 src0_sel:WORD_1
	v_pk_fma_f32 v[130:131], v[126:127], v[130:131], v[210:211] op_sel_hi:[0,1,1]
	v_pk_fma_f32 v[208:209], v[126:127], v[208:209], v[216:217] op_sel_hi:[0,1,1]
	v_pk_fma_f32 v[210:211], v[126:127], v[230:231], v[226:227] op_sel_hi:[0,1,1]
	v_pk_fma_f32 v[116:117], v[126:127], v[116:117], v[120:121] op_sel_hi:[0,1,1]
	v_cvt_pk_f32_fp8_e32 v[120:121], v118
	v_cvt_pk_f32_fp8_sdwa v[216:217], v118 src0_sel:WORD_1
	v_cvt_pk_f32_fp8_e32 v[226:227], v119
	v_cvt_pk_f32_fp8_sdwa v[118:119], v119 src0_sel:WORD_1
	v_pk_fma_f32 v[120:121], v[126:127], v[120:121], v[124:125] op_sel_hi:[0,1,1]
	v_pk_fma_f32 v[124:125], v[126:127], v[216:217], v[128:129] op_sel_hi:[0,1,1]
	v_pk_fma_f32 v[128:129], v[126:127], v[226:227], v[228:229] op_sel_hi:[0,1,1]
	v_pk_fma_f32 v[118:119], v[126:127], v[118:119], v[122:123] op_sel_hi:[0,1,1]
	s_waitcnt vmcnt(12)
	v_cvt_pk_f32_fp8_e32 v[126:127], v112
	v_cvt_pk_f32_fp8_sdwa v[216:217], v112 src0_sel:WORD_1
	v_cvt_pk_f32_fp8_e32 v[226:227], v113
	v_cvt_pk_f32_fp8_sdwa v[112:113], v113 src0_sel:WORD_1
	v_lshlrev_b32_e32 v122, 16, v206
	v_pk_fma_f32 v[126:127], v[122:123], v[126:127], v[130:131] op_sel_hi:[0,1,1]
	v_pk_fma_f32 v[130:131], v[122:123], v[216:217], v[208:209] op_sel_hi:[0,1,1]
	v_pk_fma_f32 v[208:209], v[122:123], v[226:227], v[210:211] op_sel_hi:[0,1,1]
	v_pk_fma_f32 v[112:113], v[122:123], v[112:113], v[116:117] op_sel_hi:[0,1,1]
	v_cvt_pk_f32_fp8_e32 v[116:117], v114
	v_cvt_pk_f32_fp8_sdwa v[210:211], v114 src0_sel:WORD_1
	v_cvt_pk_f32_fp8_e32 v[216:217], v115
	v_cvt_pk_f32_fp8_sdwa v[114:115], v115 src0_sel:WORD_1
	v_pk_fma_f32 v[116:117], v[122:123], v[116:117], v[120:121] op_sel_hi:[0,1,1]
	v_pk_fma_f32 v[120:121], v[122:123], v[210:211], v[124:125] op_sel_hi:[0,1,1]
	v_pk_fma_f32 v[124:125], v[122:123], v[216:217], v[128:129] op_sel_hi:[0,1,1]
	v_pk_fma_f32 v[114:115], v[122:123], v[114:115], v[118:119] op_sel_hi:[0,1,1]
	v_lshlrev_b32_e32 v118, 16, v207
	s_waitcnt vmcnt(11)
; DI void up_math(const u32x4 (&W)[16], const u32 (&pj)[16], float* __restrict__ yrow, int lane) {
;     ...
;   for (int j = 0; j < 16; ++j) {
;     const float h = __uint_as_float(pj[j] << 16);
;     const f2 hh = {h, h};
; #pragma unroll
;     for (int d = 0; d < 4; ++d) {
;       f2 lo = __builtin_amdgcn_cvt_pk_f32_fp8((int)W[j][d], false);
;       f2 hi = __builtin_amdgcn_cvt_pk_f32_fp8((int)W[j][d], true);
;       y[2 * d] = lo * hh + y[2 * d];
;       y[2 * d + 1] = hi * hh + y[2 * d + 1];
;     }
;   }
	v_cvt_pk_f32_fp8_e32 v[122:123], v108
	v_cvt_pk_f32_fp8_sdwa v[128:129], v108 src0_sel:WORD_1
	v_cvt_pk_f32_fp8_e32 v[206:207], v109
	v_cvt_pk_f32_fp8_sdwa v[108:109], v109 src0_sel:WORD_1
	v_pk_fma_f32 v[122:123], v[118:119], v[122:123], v[126:127] op_sel_hi:[0,1,1]
	v_pk_fma_f32 v[126:127], v[118:119], v[128:129], v[130:131] op_sel_hi:[0,1,1]
	v_pk_fma_f32 v[128:129], v[118:119], v[206:207], v[208:209] op_sel_hi:[0,1,1]
	v_pk_fma_f32 v[108:109], v[118:119], v[108:109], v[112:113] op_sel_hi:[0,1,1]
	v_cvt_pk_f32_fp8_e32 v[112:113], v110
	v_cvt_pk_f32_fp8_sdwa v[130:131], v110 src0_sel:WORD_1
	v_cvt_pk_f32_fp8_e32 v[206:207], v111
	v_cvt_pk_f32_fp8_sdwa v[110:111], v111 src0_sel:WORD_1
	v_pk_fma_f32 v[112:113], v[118:119], v[112:113], v[116:117] op_sel_hi:[0,1,1]
	v_pk_fma_f32 v[116:117], v[118:119], v[130:131], v[120:121] op_sel_hi:[0,1,1]
	v_pk_fma_f32 v[120:121], v[118:119], v[206:207], v[124:125] op_sel_hi:[0,1,1]
	v_pk_fma_f32 v[110:111], v[118:119], v[110:111], v[114:115] op_sel_hi:[0,1,1]
	s_waitcnt vmcnt(10)
	v_cvt_pk_f32_fp8_e32 v[118:119], v104
	v_cvt_pk_f32_fp8_sdwa v[124:125], v104 src0_sel:WORD_1
	v_cvt_pk_f32_fp8_e32 v[130:131], v105
	v_cvt_pk_f32_fp8_sdwa v[104:105], v105 src0_sel:WORD_1
	v_lshlrev_b32_e32 v114, 16, v204
	v_pk_fma_f32 v[118:119], v[114:115], v[118:119], v[122:123] op_sel_hi:[0,1,1]
	v_pk_fma_f32 v[122:123], v[114:115], v[124:125], v[126:127] op_sel_hi:[0,1,1]
	v_pk_fma_f32 v[124:125], v[114:115], v[130:131], v[128:129] op_sel_hi:[0,1,1]
	v_pk_fma_f32 v[104:105], v[114:115], v[104:105], v[108:109] op_sel_hi:[0,1,1]
	v_cvt_pk_f32_fp8_e32 v[108:109], v106
	v_cvt_pk_f32_fp8_sdwa v[126:127], v106 src0_sel:WORD_1
	v_cvt_pk_f32_fp8_e32 v[128:129], v107
	v_cvt_pk_f32_fp8_sdwa v[106:107], v107 src0_sel:WORD_1
	v_pk_fma_f32 v[108:109], v[114:115], v[108:109], v[112:113] op_sel_hi:[0,1,1]
	v_pk_fma_f32 v[112:113], v[114:115], v[126:127], v[116:117] op_sel_hi:[0,1,1]
	v_pk_fma_f32 v[116:117], v[114:115], v[128:129], v[120:121] op_sel_hi:[0,1,1]
	v_pk_fma_f32 v[106:107], v[114:115], v[106:107], v[110:111] op_sel_hi:[0,1,1]
	s_waitcnt vmcnt(9)
	v_cvt_pk_f32_fp8_e32 v[114:115], v100
	v_cvt_pk_f32_fp8_sdwa v[120:121], v100 src0_sel:WORD_1
	v_cvt_pk_f32_fp8_e32 v[126:127], v101
	v_cvt_pk_f32_fp8_sdwa v[100:101], v101 src0_sel:WORD_1
	v_lshlrev_b32_e32 v110, 16, v205
	v_pk_fma_f32 v[114:115], v[110:111], v[114:115], v[118:119] op_sel_hi:[0,1,1]
	v_pk_fma_f32 v[118:119], v[110:111], v[120:121], v[122:123] op_sel_hi:[0,1,1]
	v_pk_fma_f32 v[120:121], v[110:111], v[126:127], v[124:125] op_sel_hi:[0,1,1]
	v_pk_fma_f32 v[100:101], v[110:111], v[100:101], v[104:105] op_sel_hi:[0,1,1]
	v_cvt_pk_f32_fp8_e32 v[104:105], v102
	v_cvt_pk_f32_fp8_sdwa v[122:123], v102 src0_sel:WORD_1
	v_cvt_pk_f32_fp8_e32 v[124:125], v103
	v_cvt_pk_f32_fp8_sdwa v[102:103], v103 src0_sel:WORD_1
	v_pk_fma_f32 v[104:105], v[110:111], v[104:105], v[108:109] op_sel_hi:[0,1,1]
	v_pk_fma_f32 v[108:109], v[110:111], v[122:123], v[112:113] op_sel_hi:[0,1,1]
	v_pk_fma_f32 v[112:113], v[110:111], v[124:125], v[116:117] op_sel_hi:[0,1,1]
	v_pk_fma_f32 v[102:103], v[110:111], v[102:103], v[106:107] op_sel_hi:[0,1,1]
	s_waitcnt vmcnt(8)
	v_cvt_pk_f32_fp8_e32 v[110:111], v96
	v_cvt_pk_f32_fp8_sdwa v[116:117], v96 src0_sel:WORD_1
	v_cvt_pk_f32_fp8_e32 v[122:123], v97
	v_cvt_pk_f32_fp8_sdwa v[96:97], v97 src0_sel:WORD_1
	v_lshlrev_b32_e32 v106, 16, v202
	v_pk_fma_f32 v[110:111], v[106:107], v[110:111], v[114:115] op_sel_hi:[0,1,1]
	v_pk_fma_f32 v[114:115], v[106:107], v[116:117], v[118:119] op_sel_hi:[0,1,1]
	v_pk_fma_f32 v[116:117], v[106:107], v[122:123], v[120:121] op_sel_hi:[0,1,1]
	v_pk_fma_f32 v[96:97], v[106:107], v[96:97], v[100:101] op_sel_hi:[0,1,1]
	v_cvt_pk_f32_fp8_e32 v[100:101], v98
	v_cvt_pk_f32_fp8_sdwa v[118:119], v98 src0_sel:WORD_1
	v_cvt_pk_f32_fp8_e32 v[120:121], v99
	v_cvt_pk_f32_fp8_sdwa v[98:99], v99 src0_sel:WORD_1
	v_pk_fma_f32 v[100:101], v[106:107], v[100:101], v[104:105] op_sel_hi:[0,1,1]
	v_pk_fma_f32 v[104:105], v[106:107], v[118:119], v[108:109] op_sel_hi:[0,1,1]
	v_pk_fma_f32 v[108:109], v[106:107], v[120:121], v[112:113] op_sel_hi:[0,1,1]
	v_pk_fma_f32 v[98:99], v[106:107], v[98:99], v[102:103] op_sel_hi:[0,1,1]
	s_waitcnt vmcnt(7)
	v_cvt_pk_f32_fp8_e32 v[106:107], v92
	v_cvt_pk_f32_fp8_sdwa v[112:113], v92 src0_sel:WORD_1
	v_cvt_pk_f32_fp8_e32 v[118:119], v93
	v_cvt_pk_f32_fp8_sdwa v[92:93], v93 src0_sel:WORD_1
	v_lshlrev_b32_e32 v102, 16, v203
	v_pk_fma_f32 v[106:107], v[102:103], v[106:107], v[110:111] op_sel_hi:[0,1,1]
	v_pk_fma_f32 v[110:111], v[102:103], v[112:113], v[114:115] op_sel_hi:[0,1,1]
	v_pk_fma_f32 v[112:113], v[102:103], v[118:119], v[116:117] op_sel_hi:[0,1,1]
	v_pk_fma_f32 v[92:93], v[102:103], v[92:93], v[96:97] op_sel_hi:[0,1,1]
	v_cvt_pk_f32_fp8_e32 v[96:97], v94
	v_cvt_pk_f32_fp8_sdwa v[114:115], v94 src0_sel:WORD_1
	v_cvt_pk_f32_fp8_e32 v[116:117], v95
	v_cvt_pk_f32_fp8_sdwa v[94:95], v95 src0_sel:WORD_1
	v_pk_fma_f32 v[96:97], v[102:103], v[96:97], v[100:101] op_sel_hi:[0,1,1]
	v_pk_fma_f32 v[100:101], v[102:103], v[114:115], v[104:105] op_sel_hi:[0,1,1]
	v_pk_fma_f32 v[104:105], v[102:103], v[116:117], v[108:109] op_sel_hi:[0,1,1]
	v_pk_fma_f32 v[94:95], v[102:103], v[94:95], v[98:99] op_sel_hi:[0,1,1]
	s_waitcnt vmcnt(6)
; DI void up_math(const u32x4 (&W)[16], const u32 (&pj)[16], float* __restrict__ yrow, int lane) {
;     ...
;   for (int j = 0; j < 16; ++j) {
;     const float h = __uint_as_float(pj[j] << 16);
;     const f2 hh = {h, h};
; #pragma unroll
;     for (int d = 0; d < 4; ++d) {
;       f2 lo = __builtin_amdgcn_cvt_pk_f32_fp8((int)W[j][d], false);
;       f2 hi = __builtin_amdgcn_cvt_pk_f32_fp8((int)W[j][d], true);
;       y[2 * d] = lo * hh + y[2 * d];
;       y[2 * d + 1] = hi * hh + y[2 * d + 1];
;     }
;   }
	v_cvt_pk_f32_fp8_e32 v[102:103], v88
	v_cvt_pk_f32_fp8_sdwa v[108:109], v88 src0_sel:WORD_1
	v_cvt_pk_f32_fp8_e32 v[114:115], v89
	v_cvt_pk_f32_fp8_sdwa v[88:89], v89 src0_sel:WORD_1
	v_lshlrev_b32_e32 v98, 16, v200
	v_pk_fma_f32 v[102:103], v[98:99], v[102:103], v[106:107] op_sel_hi:[0,1,1]
	v_pk_fma_f32 v[106:107], v[98:99], v[108:109], v[110:111] op_sel_hi:[0,1,1]
	v_pk_fma_f32 v[108:109], v[98:99], v[114:115], v[112:113] op_sel_hi:[0,1,1]
	v_pk_fma_f32 v[88:89], v[98:99], v[88:89], v[92:93] op_sel_hi:[0,1,1]
	v_cvt_pk_f32_fp8_e32 v[92:93], v90
	v_cvt_pk_f32_fp8_sdwa v[110:111], v90 src0_sel:WORD_1
	v_cvt_pk_f32_fp8_e32 v[112:113], v91
	v_cvt_pk_f32_fp8_sdwa v[90:91], v91 src0_sel:WORD_1
	v_pk_fma_f32 v[92:93], v[98:99], v[92:93], v[96:97] op_sel_hi:[0,1,1]
	v_pk_fma_f32 v[96:97], v[98:99], v[110:111], v[100:101] op_sel_hi:[0,1,1]
	v_pk_fma_f32 v[100:101], v[98:99], v[112:113], v[104:105] op_sel_hi:[0,1,1]
	v_pk_fma_f32 v[90:91], v[98:99], v[90:91], v[94:95] op_sel_hi:[0,1,1]
	s_waitcnt vmcnt(5)
	v_cvt_pk_f32_fp8_e32 v[98:99], v84
	v_cvt_pk_f32_fp8_sdwa v[104:105], v84 src0_sel:WORD_1
	v_cvt_pk_f32_fp8_e32 v[110:111], v85
	v_cvt_pk_f32_fp8_sdwa v[84:85], v85 src0_sel:WORD_1
	v_lshlrev_b32_e32 v94, 16, v201
	v_pk_fma_f32 v[98:99], v[94:95], v[98:99], v[102:103] op_sel_hi:[0,1,1]
	v_pk_fma_f32 v[102:103], v[94:95], v[104:105], v[106:107] op_sel_hi:[0,1,1]
	v_pk_fma_f32 v[104:105], v[94:95], v[110:111], v[108:109] op_sel_hi:[0,1,1]
	v_pk_fma_f32 v[84:85], v[94:95], v[84:85], v[88:89] op_sel_hi:[0,1,1]
	v_cvt_pk_f32_fp8_e32 v[88:89], v86
	v_cvt_pk_f32_fp8_sdwa v[106:107], v86 src0_sel:WORD_1
	v_cvt_pk_f32_fp8_e32 v[108:109], v87
	v_cvt_pk_f32_fp8_sdwa v[86:87], v87 src0_sel:WORD_1
	v_pk_fma_f32 v[88:89], v[94:95], v[88:89], v[92:93] op_sel_hi:[0,1,1]
	v_pk_fma_f32 v[92:93], v[94:95], v[106:107], v[96:97] op_sel_hi:[0,1,1]
	v_pk_fma_f32 v[96:97], v[94:95], v[108:109], v[100:101] op_sel_hi:[0,1,1]
	v_pk_fma_f32 v[86:87], v[94:95], v[86:87], v[90:91] op_sel_hi:[0,1,1]
	s_waitcnt vmcnt(4)
	v_cvt_pk_f32_fp8_e32 v[94:95], v80
	v_cvt_pk_f32_fp8_sdwa v[100:101], v80 src0_sel:WORD_1
	v_cvt_pk_f32_fp8_e32 v[106:107], v81
	v_cvt_pk_f32_fp8_sdwa v[80:81], v81 src0_sel:WORD_1
	v_lshlrev_b32_e32 v90, 16, v198
	v_pk_fma_f32 v[94:95], v[90:91], v[94:95], v[98:99] op_sel_hi:[0,1,1]
	v_pk_fma_f32 v[98:99], v[90:91], v[100:101], v[102:103] op_sel_hi:[0,1,1]
	v_pk_fma_f32 v[100:101], v[90:91], v[106:107], v[104:105] op_sel_hi:[0,1,1]
	v_pk_fma_f32 v[80:81], v[90:91], v[80:81], v[84:85] op_sel_hi:[0,1,1]
	v_cvt_pk_f32_fp8_e32 v[84:85], v82
	v_cvt_pk_f32_fp8_sdwa v[102:103], v82 src0_sel:WORD_1
	v_cvt_pk_f32_fp8_e32 v[104:105], v83
	v_cvt_pk_f32_fp8_sdwa v[82:83], v83 src0_sel:WORD_1
	v_pk_fma_f32 v[84:85], v[90:91], v[84:85], v[88:89] op_sel_hi:[0,1,1]
	v_pk_fma_f32 v[88:89], v[90:91], v[102:103], v[92:93] op_sel_hi:[0,1,1]
	v_pk_fma_f32 v[92:93], v[90:91], v[104:105], v[96:97] op_sel_hi:[0,1,1]
	v_pk_fma_f32 v[82:83], v[90:91], v[82:83], v[86:87] op_sel_hi:[0,1,1]
	s_waitcnt vmcnt(3)
	v_cvt_pk_f32_fp8_e32 v[90:91], v76
	v_cvt_pk_f32_fp8_sdwa v[96:97], v76 src0_sel:WORD_1
	v_cvt_pk_f32_fp8_e32 v[102:103], v77
	v_cvt_pk_f32_fp8_sdwa v[76:77], v77 src0_sel:WORD_1
	v_lshlrev_b32_e32 v86, 16, v199
	v_pk_fma_f32 v[90:91], v[86:87], v[90:91], v[94:95] op_sel_hi:[0,1,1]
	v_pk_fma_f32 v[94:95], v[86:87], v[96:97], v[98:99] op_sel_hi:[0,1,1]
	v_pk_fma_f32 v[96:97], v[86:87], v[102:103], v[100:101] op_sel_hi:[0,1,1]
	v_pk_fma_f32 v[76:77], v[86:87], v[76:77], v[80:81] op_sel_hi:[0,1,1]
	v_cvt_pk_f32_fp8_e32 v[80:81], v78
	v_cvt_pk_f32_fp8_sdwa v[98:99], v78 src0_sel:WORD_1
	v_cvt_pk_f32_fp8_e32 v[100:101], v79
	v_cvt_pk_f32_fp8_sdwa v[78:79], v79 src0_sel:WORD_1
	v_pk_fma_f32 v[80:81], v[86:87], v[80:81], v[84:85] op_sel_hi:[0,1,1]
	v_pk_fma_f32 v[84:85], v[86:87], v[98:99], v[88:89] op_sel_hi:[0,1,1]
	v_pk_fma_f32 v[88:89], v[86:87], v[100:101], v[92:93] op_sel_hi:[0,1,1]
	v_pk_fma_f32 v[78:79], v[86:87], v[78:79], v[82:83] op_sel_hi:[0,1,1]
	s_waitcnt vmcnt(2)
	v_cvt_pk_f32_fp8_e32 v[86:87], v72
	v_cvt_pk_f32_fp8_sdwa v[92:93], v72 src0_sel:WORD_1
	v_cvt_pk_f32_fp8_e32 v[98:99], v73
	v_cvt_pk_f32_fp8_sdwa v[72:73], v73 src0_sel:WORD_1
	v_lshlrev_b32_e32 v82, 16, v196
	v_pk_fma_f32 v[86:87], v[82:83], v[86:87], v[90:91] op_sel_hi:[0,1,1]
	v_pk_fma_f32 v[90:91], v[82:83], v[92:93], v[94:95] op_sel_hi:[0,1,1]
	v_pk_fma_f32 v[92:93], v[82:83], v[98:99], v[96:97] op_sel_hi:[0,1,1]
	v_pk_fma_f32 v[72:73], v[82:83], v[72:73], v[76:77] op_sel_hi:[0,1,1]
	v_cvt_pk_f32_fp8_e32 v[76:77], v74
	v_cvt_pk_f32_fp8_sdwa v[94:95], v74 src0_sel:WORD_1
	v_cvt_pk_f32_fp8_e32 v[96:97], v75
	v_cvt_pk_f32_fp8_sdwa v[74:75], v75 src0_sel:WORD_1
	v_pk_fma_f32 v[76:77], v[82:83], v[76:77], v[80:81] op_sel_hi:[0,1,1]
	v_pk_fma_f32 v[80:81], v[82:83], v[94:95], v[84:85] op_sel_hi:[0,1,1]
	v_pk_fma_f32 v[84:85], v[82:83], v[96:97], v[88:89] op_sel_hi:[0,1,1]
	v_pk_fma_f32 v[74:75], v[82:83], v[74:75], v[78:79] op_sel_hi:[0,1,1]
	s_waitcnt vmcnt(1)
; DI void up_issue(u32x4 (&W)[16], u32 (&pj)[16], const u32* pl, const unsigned char* wbase, int grp) {
; #pragma unroll
;   for (int j = 0; j < 16; ++j) {
;     pj[j] = pl[8 * j + grp];
;     W[j] = *(const u32x4*)(wbase + (size_t)(pj[j] >> 16) * 1024);
;   }
; DI void up_math(const u32x4 (&W)[16], const u32 (&pj)[16], float* __restrict__ yrow, int lane) {
;     ...
;   const bool b5 = lane & 32, b4 = lane & 16, b3 = lane & 8;
;   f2 q4[4];
; #pragma unroll
;   for (int i = 0; i < 4; ++i) {
;     f2 snd = b5 ? y[i] : y[i + 4]; f2 kp = b5 ? y[i + 4] : y[i];
;     q4[i] = f2{kp.x + __shfl_xor(snd.x, 32), kp.y + __shfl_xor(snd.y, 32)};
;   }
;   f2 r2[2];
; #pragma unroll
;   for (int i = 0; i < 2; ++i) {
;     f2 snd = b4 ? q4[i] : q4[i + 2]; f2 kp = b4 ? q4[i + 2] : q4[i];
;     r2[i] = f2{kp.x + __shfl_xor(snd.x, 16), kp.y + __shfl_xor(snd.y, 16)};
;   }
;   f2 a;
;   { f2 snd = b3 ? r2[0] : r2[1]; f2 kp = b3 ? r2[1] : r2[0]; a = f2{kp.x + __shfl_xor(snd.x, 8), kp.y + __shfl_xor(snd.y, 8)}; }
;   const int ci = (b5 ? 4 : 0) + (b4 ? 2 : 0) + (b3 ? 1 : 0);
;   *(float2*)(yrow + (lane & 7) * 16 + 2 * ci) = make_float2(a.x, a.y);
	v_cvt_pk_f32_fp8_e32 v[82:83], v68
	v_cvt_pk_f32_fp8_sdwa v[88:89], v68 src0_sel:WORD_1
	v_cvt_pk_f32_fp8_e32 v[94:95], v69
	v_cvt_pk_f32_fp8_sdwa v[68:69], v69 src0_sel:WORD_1
	v_lshlrev_b32_e32 v78, 16, v197
	v_pk_fma_f32 v[82:83], v[78:79], v[82:83], v[86:87] op_sel_hi:[0,1,1]
	v_pk_fma_f32 v[86:87], v[78:79], v[88:89], v[90:91] op_sel_hi:[0,1,1]
	v_pk_fma_f32 v[68:69], v[78:79], v[68:69], v[72:73] op_sel_hi:[0,1,1]
	v_cvt_pk_f32_fp8_e32 v[72:73], v70
	v_pk_fma_f32 v[88:89], v[78:79], v[94:95], v[92:93] op_sel_hi:[0,1,1]
	v_cvt_pk_f32_fp8_sdwa v[90:91], v70 src0_sel:WORD_1
	v_cvt_pk_f32_fp8_e32 v[92:93], v71
	v_cvt_pk_f32_fp8_sdwa v[70:71], v71 src0_sel:WORD_1
	v_pk_fma_f32 v[72:73], v[78:79], v[72:73], v[76:77] op_sel_hi:[0,1,1]
	v_pk_fma_f32 v[76:77], v[78:79], v[90:91], v[80:81] op_sel_hi:[0,1,1]
	v_pk_fma_f32 v[80:81], v[78:79], v[92:93], v[84:85] op_sel_hi:[0,1,1]
	v_pk_fma_f32 v[70:71], v[78:79], v[70:71], v[74:75] op_sel_hi:[0,1,1]
	s_nop 1
	v_permlane32_swap_b32_e32 v82, v72
	v_permlane32_swap_b32_e32 v83, v73
	v_permlane32_swap_b32_e32 v86, v76
	v_permlane32_swap_b32_e32 v87, v77
	v_permlane32_swap_b32_e32 v88, v80
	v_permlane32_swap_b32_e32 v89, v81
	v_permlane32_swap_b32_e32 v68, v70
	v_permlane32_swap_b32_e32 v69, v71
	v_pk_add_f32 v[72:73], v[82:83], v[72:73]
	v_pk_add_f32 v[74:75], v[86:87], v[76:77]
	v_pk_add_f32 v[76:77], v[88:89], v[80:81]
	v_pk_add_f32 v[68:69], v[68:69], v[70:71]
	s_nop 1
	v_permlane16_swap_b32_e32 v72, v76
	v_permlane16_swap_b32_e32 v73, v77
	v_permlane16_swap_b32_e32 v74, v68
	v_permlane16_swap_b32_e32 v75, v69
	v_pk_add_f32 v[70:71], v[72:73], v[76:77]
	v_pk_add_f32 v[68:69], v[74:75], v[68:69]
	s_nop 1
	v_add_f32_dpp v68, v68, v68 row_shr:8 row_mask:0xf bank_mask:0xc
	v_add_f32_dpp v69, v69, v69 row_shr:8 row_mask:0xf bank_mask:0xc
	v_add_f32_dpp v68, v70, v70 row_shl:8 row_mask:0xf bank_mask:0x3
	v_add_f32_dpp v69, v71, v71 row_shl:8 row_mask:0xf bank_mask:0x3
	v_add_co_u32_e32 v70, vcc, 0x1000, v188
	v_addc_co_u32_e32 v71, vcc, 0, v189, vcc
	global_store_dwordx2 v[70:71], v[68:69], off
	v_add_u32_e32 v145, 0x400, v145
	v_lshl_add_u64 v[188:189], v[188:189], 0, s[18:19]
	s_and_b64 vcc, exec, s[28:29]
	s_cbranch_vccnz .LBB0_1637
.LBB0_1650:
	ds_read2_b32 v[210:211], v145 offset1:8
	ds_read2_b32 v[208:209], v145 offset0:16 offset1:24
	s_waitcnt lgkmcnt(1)
	v_lshlrev_b32_sdwa v132, v215, v210 dst_sel:DWORD dst_unused:UNUSED_PAD src0_sel:DWORD src1_sel:WORD_1
	v_lshl_add_u64 v[68:69], v[174:175], 0, v[132:133]
	v_lshlrev_b32_sdwa v132, v215, v211 dst_sel:DWORD dst_unused:UNUSED_PAD src0_sel:DWORD src1_sel:WORD_1
	v_lshl_add_u64 v[70:71], v[174:175], 0, v[132:133]
	s_waitcnt lgkmcnt(0)
	v_lshlrev_b32_sdwa v132, v215, v208 dst_sel:DWORD dst_unused:UNUSED_PAD src0_sel:DWORD src1_sel:WORD_1
	global_load_dwordx4 v[128:131], v[68:69], off
	global_load_dwordx4 v[124:127], v[70:71], off
	ds_read2_b32 v[206:207], v145 offset0:32 offset1:40
	v_lshl_add_u64 v[68:69], v[174:175], 0, v[132:133]
	v_lshlrev_b32_sdwa v132, v215, v209 dst_sel:DWORD dst_unused:UNUSED_PAD src0_sel:DWORD src1_sel:WORD_1
	v_lshl_add_u64 v[70:71], v[174:175], 0, v[132:133]
	global_load_dwordx4 v[120:123], v[68:69], off
	global_load_dwordx4 v[116:119], v[70:71], off
	ds_read2_b32 v[204:205], v145 offset0:48 offset1:56
	s_waitcnt lgkmcnt(1)
	v_lshlrev_b32_sdwa v132, v215, v206 dst_sel:DWORD dst_unused:UNUSED_PAD src0_sel:DWORD src1_sel:WORD_1
	v_lshl_add_u64 v[68:69], v[174:175], 0, v[132:133]
	v_lshlrev_b32_sdwa v132, v215, v207 dst_sel:DWORD dst_unused:UNUSED_PAD src0_sel:DWORD src1_sel:WORD_1
	v_lshl_add_u64 v[70:71], v[174:175], 0, v[132:133]
	global_load_dwordx4 v[112:115], v[68:69], off
	global_load_dwordx4 v[108:111], v[70:71], off
	s_waitcnt lgkmcnt(0)
	v_lshlrev_b32_sdwa v132, v215, v204 dst_sel:DWORD dst_unused:UNUSED_PAD src0_sel:DWORD src1_sel:WORD_1
	ds_read2_b32 v[202:203], v145 offset0:64 offset1:72
	v_lshl_add_u64 v[68:69], v[174:175], 0, v[132:133]
	v_lshlrev_b32_sdwa v132, v215, v205 dst_sel:DWORD dst_unused:UNUSED_PAD src0_sel:DWORD src1_sel:WORD_1
	v_lshl_add_u64 v[70:71], v[174:175], 0, v[132:133]
	global_load_dwordx4 v[104:107], v[68:69], off
	global_load_dwordx4 v[100:103], v[70:71], off
	ds_read2_b32 v[200:201], v145 offset0:80 offset1:88
	s_waitcnt lgkmcnt(1)
	v_lshlrev_b32_sdwa v132, v215, v202 dst_sel:DWORD dst_unused:UNUSED_PAD src0_sel:DWORD src1_sel:WORD_1
	v_lshl_add_u64 v[68:69], v[174:175], 0, v[132:133]
	v_lshlrev_b32_sdwa v132, v215, v203 dst_sel:DWORD dst_unused:UNUSED_PAD src0_sel:DWORD src1_sel:WORD_1
	v_lshl_add_u64 v[70:71], v[174:175], 0, v[132:133]
	global_load_dwordx4 v[96:99], v[68:69], off
	global_load_dwordx4 v[92:95], v[70:71], off
	s_waitcnt lgkmcnt(0)
	v_lshlrev_b32_sdwa v132, v215, v200 dst_sel:DWORD dst_unused:UNUSED_PAD src0_sel:DWORD src1_sel:WORD_1
	ds_read2_b32 v[198:199], v145 offset0:96 offset1:104
	v_lshl_add_u64 v[68:69], v[174:175], 0, v[132:133]
	v_lshlrev_b32_sdwa v132, v215, v201 dst_sel:DWORD dst_unused:UNUSED_PAD src0_sel:DWORD src1_sel:WORD_1
	v_lshl_add_u64 v[70:71], v[174:175], 0, v[132:133]
	global_load_dwordx4 v[88:91], v[68:69], off
	global_load_dwordx4 v[84:87], v[70:71], off
	ds_read2_b32 v[196:197], v145 offset0:112 offset1:120
	s_waitcnt lgkmcnt(1)
	v_lshlrev_b32_sdwa v132, v215, v198 dst_sel:DWORD dst_unused:UNUSED_PAD src0_sel:DWORD src1_sel:WORD_1
	v_lshl_add_u64 v[68:69], v[174:175], 0, v[132:133]
	v_lshlrev_b32_sdwa v132, v215, v199 dst_sel:DWORD dst_unused:UNUSED_PAD src0_sel:DWORD src1_sel:WORD_1
	v_lshl_add_u64 v[70:71], v[174:175], 0, v[132:133]
	s_waitcnt lgkmcnt(0)
; DI void up_issue(u32x4 (&W)[16], u32 (&pj)[16], const u32* pl, const unsigned char* wbase, int grp) {
; #pragma unroll
;   for (int j = 0; j < 16; ++j) {
;     pj[j] = pl[8 * j + grp];
;     W[j] = *(const u32x4*)(wbase + (size_t)(pj[j] >> 16) * 1024);
;   }
; }
; DI void up_math(const u32x4 (&W)[16], const u32 (&pj)[16], float* __restrict__ yrow, int lane) {
;   f2 y[8];
; #pragma unroll
;   for (int i = 0; i < 8; ++i) y[i] = f2{0.f, 0.f};
; #pragma unroll
;   for (int j = 0; j < 16; ++j) {
;     const float h = __uint_as_float(pj[j] << 16);
;     const f2 hh = {h, h};
; #pragma unroll
;     for (int d = 0; d < 4; ++d) {
;       f2 lo = __builtin_amdgcn_cvt_pk_f32_fp8((int)W[j][d], false);
;       f2 hi = __builtin_amdgcn_cvt_pk_f32_fp8((int)W[j][d], true);
;       y[2 * d] = lo * hh + y[2 * d];
;       y[2 * d + 1] = hi * hh + y[2 * d + 1];
;     }
;   }
	v_lshlrev_b32_sdwa v132, v215, v196 dst_sel:DWORD dst_unused:UNUSED_PAD src0_sel:DWORD src1_sel:WORD_1
	global_load_dwordx4 v[80:83], v[68:69], off
	global_load_dwordx4 v[76:79], v[70:71], off
	v_lshl_add_u64 v[68:69], v[174:175], 0, v[132:133]
	v_lshlrev_b32_sdwa v132, v215, v197 dst_sel:DWORD dst_unused:UNUSED_PAD src0_sel:DWORD src1_sel:WORD_1
	v_lshl_add_u64 v[70:71], v[174:175], 0, v[132:133]
	global_load_dwordx4 v[72:75], v[68:69], off
	s_nop 0
	global_load_dwordx4 v[68:71], v[70:71], off
	s_waitcnt vmcnt(31)
	v_cvt_pk_f32_fp8_e32 v[216:217], v4
	v_cvt_pk_f32_fp8_sdwa v[226:227], v4 src0_sel:WORD_1
	v_cvt_pk_f32_fp8_e32 v[228:229], v5
	v_cvt_pk_f32_fp8_sdwa v[230:231], v5 src0_sel:WORD_1
	v_cvt_pk_f32_fp8_e32 v[232:233], v6
	v_cvt_pk_f32_fp8_sdwa v[234:235], v6 src0_sel:WORD_1
	v_cvt_pk_f32_fp8_e32 v[236:237], v7
	v_cvt_pk_f32_fp8_sdwa v[238:239], v7 src0_sel:WORD_1
	s_waitcnt vmcnt(30)
	v_cvt_pk_f32_fp8_e32 v[240:241], v8
	v_cvt_pk_f32_fp8_sdwa v[242:243], v8 src0_sel:WORD_1
	v_cvt_pk_f32_fp8_e32 v[244:245], v9
	v_cvt_pk_f32_fp8_sdwa v[246:247], v9 src0_sel:WORD_1
	v_lshlrev_b32_e32 v132, 16, v178
	v_pk_fma_f32 v[216:217], v[132:133], v[216:217], 0 op_sel_hi:[0,1,0]
	v_pk_fma_f32 v[226:227], v[132:133], v[226:227], 0 op_sel_hi:[0,1,0]
	v_pk_fma_f32 v[228:229], v[132:133], v[228:229], 0 op_sel_hi:[0,1,0]
	v_pk_fma_f32 v[230:231], v[132:133], v[230:231], 0 op_sel_hi:[0,1,0]
	v_pk_fma_f32 v[232:233], v[132:133], v[232:233], 0 op_sel_hi:[0,1,0]
	v_pk_fma_f32 v[234:235], v[132:133], v[234:235], 0 op_sel_hi:[0,1,0]
	v_pk_fma_f32 v[236:237], v[132:133], v[236:237], 0 op_sel_hi:[0,1,0]
	v_pk_fma_f32 v[238:239], v[132:133], v[238:239], 0 op_sel_hi:[0,1,0]
	v_lshlrev_b32_e32 v132, 16, v179
	v_pk_fma_f32 v[216:217], v[132:133], v[240:241], v[216:217] op_sel_hi:[0,1,1]
	v_cvt_pk_f32_fp8_e32 v[240:241], v10
	v_pk_fma_f32 v[226:227], v[132:133], v[242:243], v[226:227] op_sel_hi:[0,1,1]
	v_pk_fma_f32 v[228:229], v[132:133], v[244:245], v[228:229] op_sel_hi:[0,1,1]
	v_pk_fma_f32 v[230:231], v[132:133], v[246:247], v[230:231] op_sel_hi:[0,1,1]
	v_cvt_pk_f32_fp8_sdwa v[242:243], v10 src0_sel:WORD_1
	v_cvt_pk_f32_fp8_e32 v[244:245], v11
	v_cvt_pk_f32_fp8_sdwa v[246:247], v11 src0_sel:WORD_1
	v_pk_fma_f32 v[232:233], v[132:133], v[240:241], v[232:233] op_sel_hi:[0,1,1]
	s_waitcnt vmcnt(29)
	v_cvt_pk_f32_fp8_e32 v[240:241], v12
	v_pk_fma_f32 v[234:235], v[132:133], v[242:243], v[234:235] op_sel_hi:[0,1,1]
	v_pk_fma_f32 v[236:237], v[132:133], v[244:245], v[236:237] op_sel_hi:[0,1,1]
	v_pk_fma_f32 v[238:239], v[132:133], v[246:247], v[238:239] op_sel_hi:[0,1,1]
	v_cvt_pk_f32_fp8_sdwa v[242:243], v12 src0_sel:WORD_1
	v_cvt_pk_f32_fp8_e32 v[244:245], v13
	v_cvt_pk_f32_fp8_sdwa v[246:247], v13 src0_sel:WORD_1
	v_lshlrev_b32_e32 v132, 16, v180
	v_pk_fma_f32 v[216:217], v[132:133], v[240:241], v[216:217] op_sel_hi:[0,1,1]
	v_cvt_pk_f32_fp8_e32 v[240:241], v14
	v_pk_fma_f32 v[226:227], v[132:133], v[242:243], v[226:227] op_sel_hi:[0,1,1]
	v_pk_fma_f32 v[228:229], v[132:133], v[244:245], v[228:229] op_sel_hi:[0,1,1]
	v_pk_fma_f32 v[230:231], v[132:133], v[246:247], v[230:231] op_sel_hi:[0,1,1]
	v_cvt_pk_f32_fp8_sdwa v[242:243], v14 src0_sel:WORD_1
	v_cvt_pk_f32_fp8_e32 v[244:245], v15
	v_cvt_pk_f32_fp8_sdwa v[246:247], v15 src0_sel:WORD_1
	v_pk_fma_f32 v[232:233], v[132:133], v[240:241], v[232:233] op_sel_hi:[0,1,1]
	s_waitcnt vmcnt(28)
	v_cvt_pk_f32_fp8_e32 v[240:241], v16
	v_pk_fma_f32 v[234:235], v[132:133], v[242:243], v[234:235] op_sel_hi:[0,1,1]
	v_pk_fma_f32 v[236:237], v[132:133], v[244:245], v[236:237] op_sel_hi:[0,1,1]
	v_pk_fma_f32 v[238:239], v[132:133], v[246:247], v[238:239] op_sel_hi:[0,1,1]
	v_cvt_pk_f32_fp8_sdwa v[242:243], v16 src0_sel:WORD_1
	v_cvt_pk_f32_fp8_e32 v[244:245], v17
	v_cvt_pk_f32_fp8_sdwa v[246:247], v17 src0_sel:WORD_1
	v_lshlrev_b32_e32 v132, 16, v181
	v_pk_fma_f32 v[216:217], v[132:133], v[240:241], v[216:217] op_sel_hi:[0,1,1]
	v_cvt_pk_f32_fp8_e32 v[240:241], v18
	v_pk_fma_f32 v[226:227], v[132:133], v[242:243], v[226:227] op_sel_hi:[0,1,1]
	v_pk_fma_f32 v[228:229], v[132:133], v[244:245], v[228:229] op_sel_hi:[0,1,1]
	v_pk_fma_f32 v[230:231], v[132:133], v[246:247], v[230:231] op_sel_hi:[0,1,1]
	v_cvt_pk_f32_fp8_sdwa v[242:243], v18 src0_sel:WORD_1
	v_cvt_pk_f32_fp8_e32 v[244:245], v19
	v_cvt_pk_f32_fp8_sdwa v[246:247], v19 src0_sel:WORD_1
	v_pk_fma_f32 v[232:233], v[132:133], v[240:241], v[232:233] op_sel_hi:[0,1,1]
	s_waitcnt vmcnt(27)
	v_cvt_pk_f32_fp8_e32 v[240:241], v20
	v_pk_fma_f32 v[234:235], v[132:133], v[242:243], v[234:235] op_sel_hi:[0,1,1]
	v_pk_fma_f32 v[236:237], v[132:133], v[244:245], v[236:237] op_sel_hi:[0,1,1]
	v_pk_fma_f32 v[238:239], v[132:133], v[246:247], v[238:239] op_sel_hi:[0,1,1]
	v_cvt_pk_f32_fp8_sdwa v[242:243], v20 src0_sel:WORD_1
	v_cvt_pk_f32_fp8_e32 v[244:245], v21
	v_cvt_pk_f32_fp8_sdwa v[246:247], v21 src0_sel:WORD_1
	v_lshlrev_b32_e32 v132, 16, v182
	v_pk_fma_f32 v[216:217], v[132:133], v[240:241], v[216:217] op_sel_hi:[0,1,1]
	v_cvt_pk_f32_fp8_e32 v[240:241], v22
	v_pk_fma_f32 v[226:227], v[132:133], v[242:243], v[226:227] op_sel_hi:[0,1,1]
	v_pk_fma_f32 v[228:229], v[132:133], v[244:245], v[228:229] op_sel_hi:[0,1,1]
	v_pk_fma_f32 v[230:231], v[132:133], v[246:247], v[230:231] op_sel_hi:[0,1,1]
	v_cvt_pk_f32_fp8_sdwa v[242:243], v22 src0_sel:WORD_1
	v_cvt_pk_f32_fp8_e32 v[244:245], v23
	v_cvt_pk_f32_fp8_sdwa v[246:247], v23 src0_sel:WORD_1
	v_pk_fma_f32 v[232:233], v[132:133], v[240:241], v[232:233] op_sel_hi:[0,1,1]
	s_waitcnt vmcnt(26)
; DI void up_math(const u32x4 (&W)[16], const u32 (&pj)[16], float* __restrict__ yrow, int lane) {
;     ...
;   for (int j = 0; j < 16; ++j) {
;     const float h = __uint_as_float(pj[j] << 16);
;     const f2 hh = {h, h};
; #pragma unroll
;     for (int d = 0; d < 4; ++d) {
;       f2 lo = __builtin_amdgcn_cvt_pk_f32_fp8((int)W[j][d], false);
;       f2 hi = __builtin_amdgcn_cvt_pk_f32_fp8((int)W[j][d], true);
;       y[2 * d] = lo * hh + y[2 * d];
;       y[2 * d + 1] = hi * hh + y[2 * d + 1];
;     }
;   }
	v_cvt_pk_f32_fp8_e32 v[240:241], v24
	v_pk_fma_f32 v[234:235], v[132:133], v[242:243], v[234:235] op_sel_hi:[0,1,1]
	v_pk_fma_f32 v[236:237], v[132:133], v[244:245], v[236:237] op_sel_hi:[0,1,1]
	v_pk_fma_f32 v[238:239], v[132:133], v[246:247], v[238:239] op_sel_hi:[0,1,1]
	v_cvt_pk_f32_fp8_sdwa v[242:243], v24 src0_sel:WORD_1
	v_cvt_pk_f32_fp8_e32 v[244:245], v25
	v_cvt_pk_f32_fp8_sdwa v[246:247], v25 src0_sel:WORD_1
	v_lshlrev_b32_e32 v132, 16, v183
	v_pk_fma_f32 v[216:217], v[132:133], v[240:241], v[216:217] op_sel_hi:[0,1,1]
	v_cvt_pk_f32_fp8_e32 v[240:241], v26
	v_pk_fma_f32 v[226:227], v[132:133], v[242:243], v[226:227] op_sel_hi:[0,1,1]
	v_pk_fma_f32 v[228:229], v[132:133], v[244:245], v[228:229] op_sel_hi:[0,1,1]
	v_pk_fma_f32 v[230:231], v[132:133], v[246:247], v[230:231] op_sel_hi:[0,1,1]
	v_cvt_pk_f32_fp8_sdwa v[242:243], v26 src0_sel:WORD_1
	v_cvt_pk_f32_fp8_e32 v[244:245], v27
	v_cvt_pk_f32_fp8_sdwa v[246:247], v27 src0_sel:WORD_1
	v_pk_fma_f32 v[232:233], v[132:133], v[240:241], v[232:233] op_sel_hi:[0,1,1]
	s_waitcnt vmcnt(25)
	v_cvt_pk_f32_fp8_e32 v[240:241], v28
	v_pk_fma_f32 v[234:235], v[132:133], v[242:243], v[234:235] op_sel_hi:[0,1,1]
	v_pk_fma_f32 v[236:237], v[132:133], v[244:245], v[236:237] op_sel_hi:[0,1,1]
	v_pk_fma_f32 v[238:239], v[132:133], v[246:247], v[238:239] op_sel_hi:[0,1,1]
	v_cvt_pk_f32_fp8_sdwa v[242:243], v28 src0_sel:WORD_1
	v_cvt_pk_f32_fp8_e32 v[244:245], v29
	v_cvt_pk_f32_fp8_sdwa v[246:247], v29 src0_sel:WORD_1
	v_lshlrev_b32_e32 v132, 16, v184
	v_pk_fma_f32 v[216:217], v[132:133], v[240:241], v[216:217] op_sel_hi:[0,1,1]
	v_cvt_pk_f32_fp8_e32 v[240:241], v30
	v_pk_fma_f32 v[226:227], v[132:133], v[242:243], v[226:227] op_sel_hi:[0,1,1]
	v_pk_fma_f32 v[228:229], v[132:133], v[244:245], v[228:229] op_sel_hi:[0,1,1]
	v_pk_fma_f32 v[230:231], v[132:133], v[246:247], v[230:231] op_sel_hi:[0,1,1]
	v_cvt_pk_f32_fp8_sdwa v[242:243], v30 src0_sel:WORD_1
	v_cvt_pk_f32_fp8_e32 v[244:245], v31
	v_cvt_pk_f32_fp8_sdwa v[246:247], v31 src0_sel:WORD_1
	v_pk_fma_f32 v[232:233], v[132:133], v[240:241], v[232:233] op_sel_hi:[0,1,1]
	s_waitcnt vmcnt(24)
	v_cvt_pk_f32_fp8_e32 v[240:241], v32
	v_pk_fma_f32 v[234:235], v[132:133], v[242:243], v[234:235] op_sel_hi:[0,1,1]
	v_pk_fma_f32 v[236:237], v[132:133], v[244:245], v[236:237] op_sel_hi:[0,1,1]
	v_pk_fma_f32 v[238:239], v[132:133], v[246:247], v[238:239] op_sel_hi:[0,1,1]
	v_cvt_pk_f32_fp8_sdwa v[242:243], v32 src0_sel:WORD_1
	v_cvt_pk_f32_fp8_e32 v[244:245], v33
	v_cvt_pk_f32_fp8_sdwa v[246:247], v33 src0_sel:WORD_1
	v_lshlrev_b32_e32 v132, 16, v185
	v_pk_fma_f32 v[216:217], v[132:133], v[240:241], v[216:217] op_sel_hi:[0,1,1]
	v_cvt_pk_f32_fp8_e32 v[240:241], v34
	v_pk_fma_f32 v[226:227], v[132:133], v[242:243], v[226:227] op_sel_hi:[0,1,1]
	v_pk_fma_f32 v[228:229], v[132:133], v[244:245], v[228:229] op_sel_hi:[0,1,1]
	v_pk_fma_f32 v[230:231], v[132:133], v[246:247], v[230:231] op_sel_hi:[0,1,1]
	v_cvt_pk_f32_fp8_sdwa v[242:243], v34 src0_sel:WORD_1
	v_cvt_pk_f32_fp8_e32 v[244:245], v35
	v_cvt_pk_f32_fp8_sdwa v[246:247], v35 src0_sel:WORD_1
	v_pk_fma_f32 v[232:233], v[132:133], v[240:241], v[232:233] op_sel_hi:[0,1,1]
	s_waitcnt vmcnt(23)
	v_cvt_pk_f32_fp8_e32 v[240:241], v36
	v_pk_fma_f32 v[234:235], v[132:133], v[242:243], v[234:235] op_sel_hi:[0,1,1]
	v_pk_fma_f32 v[236:237], v[132:133], v[244:245], v[236:237] op_sel_hi:[0,1,1]
	v_pk_fma_f32 v[238:239], v[132:133], v[246:247], v[238:239] op_sel_hi:[0,1,1]
	v_cvt_pk_f32_fp8_sdwa v[242:243], v36 src0_sel:WORD_1
	v_cvt_pk_f32_fp8_e32 v[244:245], v37
	v_cvt_pk_f32_fp8_sdwa v[246:247], v37 src0_sel:WORD_1
	v_lshlrev_b32_e32 v132, 16, v186
	v_pk_fma_f32 v[216:217], v[132:133], v[240:241], v[216:217] op_sel_hi:[0,1,1]
	v_cvt_pk_f32_fp8_e32 v[240:241], v38
	v_pk_fma_f32 v[226:227], v[132:133], v[242:243], v[226:227] op_sel_hi:[0,1,1]
	v_pk_fma_f32 v[228:229], v[132:133], v[244:245], v[228:229] op_sel_hi:[0,1,1]
	v_pk_fma_f32 v[230:231], v[132:133], v[246:247], v[230:231] op_sel_hi:[0,1,1]
	v_cvt_pk_f32_fp8_sdwa v[242:243], v38 src0_sel:WORD_1
	v_cvt_pk_f32_fp8_e32 v[244:245], v39
	v_cvt_pk_f32_fp8_sdwa v[246:247], v39 src0_sel:WORD_1
	v_pk_fma_f32 v[232:233], v[132:133], v[240:241], v[232:233] op_sel_hi:[0,1,1]
	s_waitcnt vmcnt(22)
	v_cvt_pk_f32_fp8_e32 v[240:241], v40
	v_pk_fma_f32 v[234:235], v[132:133], v[242:243], v[234:235] op_sel_hi:[0,1,1]
	v_pk_fma_f32 v[236:237], v[132:133], v[244:245], v[236:237] op_sel_hi:[0,1,1]
	v_pk_fma_f32 v[238:239], v[132:133], v[246:247], v[238:239] op_sel_hi:[0,1,1]
	v_cvt_pk_f32_fp8_sdwa v[242:243], v40 src0_sel:WORD_1
	v_cvt_pk_f32_fp8_e32 v[244:245], v41
	v_cvt_pk_f32_fp8_sdwa v[246:247], v41 src0_sel:WORD_1
	v_lshlrev_b32_e32 v132, 16, v187
	v_pk_fma_f32 v[216:217], v[132:133], v[240:241], v[216:217] op_sel_hi:[0,1,1]
	v_cvt_pk_f32_fp8_e32 v[240:241], v42
	v_pk_fma_f32 v[226:227], v[132:133], v[242:243], v[226:227] op_sel_hi:[0,1,1]
	v_pk_fma_f32 v[228:229], v[132:133], v[244:245], v[228:229] op_sel_hi:[0,1,1]
	v_pk_fma_f32 v[230:231], v[132:133], v[246:247], v[230:231] op_sel_hi:[0,1,1]
	v_cvt_pk_f32_fp8_sdwa v[242:243], v42 src0_sel:WORD_1
	v_cvt_pk_f32_fp8_e32 v[244:245], v43
	v_cvt_pk_f32_fp8_sdwa v[246:247], v43 src0_sel:WORD_1
	v_pk_fma_f32 v[232:233], v[132:133], v[240:241], v[232:233] op_sel_hi:[0,1,1]
	s_waitcnt vmcnt(21)
; DI void up_math(const u32x4 (&W)[16], const u32 (&pj)[16], float* __restrict__ yrow, int lane) {
;     ...
;   for (int j = 0; j < 16; ++j) {
;     const float h = __uint_as_float(pj[j] << 16);
;     const f2 hh = {h, h};
; #pragma unroll
;     for (int d = 0; d < 4; ++d) {
;       f2 lo = __builtin_amdgcn_cvt_pk_f32_fp8((int)W[j][d], false);
;       f2 hi = __builtin_amdgcn_cvt_pk_f32_fp8((int)W[j][d], true);
;       y[2 * d] = lo * hh + y[2 * d];
;       y[2 * d + 1] = hi * hh + y[2 * d + 1];
;     }
;   }
	v_cvt_pk_f32_fp8_e32 v[240:241], v44
	v_pk_fma_f32 v[234:235], v[132:133], v[242:243], v[234:235] op_sel_hi:[0,1,1]
	v_pk_fma_f32 v[236:237], v[132:133], v[244:245], v[236:237] op_sel_hi:[0,1,1]
	v_pk_fma_f32 v[238:239], v[132:133], v[246:247], v[238:239] op_sel_hi:[0,1,1]
	v_cvt_pk_f32_fp8_sdwa v[242:243], v44 src0_sel:WORD_1
	v_cvt_pk_f32_fp8_e32 v[244:245], v45
	v_cvt_pk_f32_fp8_sdwa v[246:247], v45 src0_sel:WORD_1
	v_lshlrev_b32_e32 v132, 16, v190
	v_pk_fma_f32 v[216:217], v[132:133], v[240:241], v[216:217] op_sel_hi:[0,1,1]
	v_cvt_pk_f32_fp8_e32 v[240:241], v46
	v_pk_fma_f32 v[226:227], v[132:133], v[242:243], v[226:227] op_sel_hi:[0,1,1]
	v_pk_fma_f32 v[228:229], v[132:133], v[244:245], v[228:229] op_sel_hi:[0,1,1]
	v_pk_fma_f32 v[230:231], v[132:133], v[246:247], v[230:231] op_sel_hi:[0,1,1]
	v_cvt_pk_f32_fp8_sdwa v[242:243], v46 src0_sel:WORD_1
	v_cvt_pk_f32_fp8_e32 v[244:245], v47
	v_cvt_pk_f32_fp8_sdwa v[246:247], v47 src0_sel:WORD_1
	v_pk_fma_f32 v[232:233], v[132:133], v[240:241], v[232:233] op_sel_hi:[0,1,1]
	s_waitcnt vmcnt(20)
	v_cvt_pk_f32_fp8_e32 v[240:241], v48
	v_pk_fma_f32 v[234:235], v[132:133], v[242:243], v[234:235] op_sel_hi:[0,1,1]
	v_pk_fma_f32 v[236:237], v[132:133], v[244:245], v[236:237] op_sel_hi:[0,1,1]
	v_pk_fma_f32 v[238:239], v[132:133], v[246:247], v[238:239] op_sel_hi:[0,1,1]
	v_cvt_pk_f32_fp8_sdwa v[242:243], v48 src0_sel:WORD_1
	v_cvt_pk_f32_fp8_e32 v[244:245], v49
	v_cvt_pk_f32_fp8_sdwa v[246:247], v49 src0_sel:WORD_1
	v_lshlrev_b32_e32 v132, 16, v191
	v_pk_fma_f32 v[216:217], v[132:133], v[240:241], v[216:217] op_sel_hi:[0,1,1]
	v_cvt_pk_f32_fp8_e32 v[240:241], v50
	v_pk_fma_f32 v[226:227], v[132:133], v[242:243], v[226:227] op_sel_hi:[0,1,1]
	v_pk_fma_f32 v[228:229], v[132:133], v[244:245], v[228:229] op_sel_hi:[0,1,1]
	v_pk_fma_f32 v[230:231], v[132:133], v[246:247], v[230:231] op_sel_hi:[0,1,1]
	v_cvt_pk_f32_fp8_sdwa v[242:243], v50 src0_sel:WORD_1
	v_cvt_pk_f32_fp8_e32 v[244:245], v51
	v_cvt_pk_f32_fp8_sdwa v[246:247], v51 src0_sel:WORD_1
	v_pk_fma_f32 v[232:233], v[132:133], v[240:241], v[232:233] op_sel_hi:[0,1,1]
	s_waitcnt vmcnt(19)
	v_cvt_pk_f32_fp8_e32 v[240:241], v52
	v_pk_fma_f32 v[234:235], v[132:133], v[242:243], v[234:235] op_sel_hi:[0,1,1]
	v_pk_fma_f32 v[236:237], v[132:133], v[244:245], v[236:237] op_sel_hi:[0,1,1]
	v_pk_fma_f32 v[238:239], v[132:133], v[246:247], v[238:239] op_sel_hi:[0,1,1]
	v_cvt_pk_f32_fp8_sdwa v[242:243], v52 src0_sel:WORD_1
	v_cvt_pk_f32_fp8_e32 v[244:245], v53
	v_cvt_pk_f32_fp8_sdwa v[246:247], v53 src0_sel:WORD_1
	v_lshlrev_b32_e32 v132, 16, v192
	v_pk_fma_f32 v[216:217], v[132:133], v[240:241], v[216:217] op_sel_hi:[0,1,1]
	v_cvt_pk_f32_fp8_e32 v[240:241], v54
	v_pk_fma_f32 v[226:227], v[132:133], v[242:243], v[226:227] op_sel_hi:[0,1,1]
	v_pk_fma_f32 v[228:229], v[132:133], v[244:245], v[228:229] op_sel_hi:[0,1,1]
	v_pk_fma_f32 v[230:231], v[132:133], v[246:247], v[230:231] op_sel_hi:[0,1,1]
	v_cvt_pk_f32_fp8_sdwa v[242:243], v54 src0_sel:WORD_1
	v_cvt_pk_f32_fp8_e32 v[244:245], v55
	v_cvt_pk_f32_fp8_sdwa v[246:247], v55 src0_sel:WORD_1
	v_pk_fma_f32 v[232:233], v[132:133], v[240:241], v[232:233] op_sel_hi:[0,1,1]
	s_waitcnt vmcnt(18)
	v_cvt_pk_f32_fp8_e32 v[240:241], v56
	v_pk_fma_f32 v[234:235], v[132:133], v[242:243], v[234:235] op_sel_hi:[0,1,1]
	v_pk_fma_f32 v[236:237], v[132:133], v[244:245], v[236:237] op_sel_hi:[0,1,1]
	v_pk_fma_f32 v[238:239], v[132:133], v[246:247], v[238:239] op_sel_hi:[0,1,1]
	v_cvt_pk_f32_fp8_sdwa v[242:243], v56 src0_sel:WORD_1
	v_cvt_pk_f32_fp8_e32 v[244:245], v57
	v_cvt_pk_f32_fp8_sdwa v[246:247], v57 src0_sel:WORD_1
	v_lshlrev_b32_e32 v132, 16, v193
	v_pk_fma_f32 v[216:217], v[132:133], v[240:241], v[216:217] op_sel_hi:[0,1,1]
	v_cvt_pk_f32_fp8_e32 v[240:241], v58
	v_pk_fma_f32 v[226:227], v[132:133], v[242:243], v[226:227] op_sel_hi:[0,1,1]
	v_pk_fma_f32 v[228:229], v[132:133], v[244:245], v[228:229] op_sel_hi:[0,1,1]
	v_pk_fma_f32 v[230:231], v[132:133], v[246:247], v[230:231] op_sel_hi:[0,1,1]
	v_cvt_pk_f32_fp8_sdwa v[242:243], v58 src0_sel:WORD_1
	v_cvt_pk_f32_fp8_e32 v[244:245], v59
	v_cvt_pk_f32_fp8_sdwa v[246:247], v59 src0_sel:WORD_1
	v_pk_fma_f32 v[232:233], v[132:133], v[240:241], v[232:233] op_sel_hi:[0,1,1]
	s_waitcnt vmcnt(17)
	v_cvt_pk_f32_fp8_e32 v[240:241], v60
	v_pk_fma_f32 v[234:235], v[132:133], v[242:243], v[234:235] op_sel_hi:[0,1,1]
	v_pk_fma_f32 v[236:237], v[132:133], v[244:245], v[236:237] op_sel_hi:[0,1,1]
	v_pk_fma_f32 v[238:239], v[132:133], v[246:247], v[238:239] op_sel_hi:[0,1,1]
	v_cvt_pk_f32_fp8_sdwa v[242:243], v60 src0_sel:WORD_1
	v_cvt_pk_f32_fp8_e32 v[244:245], v61
	v_cvt_pk_f32_fp8_sdwa v[246:247], v61 src0_sel:WORD_1
	v_lshlrev_b32_e32 v132, 16, v194
	v_pk_fma_f32 v[216:217], v[132:133], v[240:241], v[216:217] op_sel_hi:[0,1,1]
	v_cvt_pk_f32_fp8_e32 v[240:241], v62
	v_pk_fma_f32 v[226:227], v[132:133], v[242:243], v[226:227] op_sel_hi:[0,1,1]
	v_pk_fma_f32 v[228:229], v[132:133], v[244:245], v[228:229] op_sel_hi:[0,1,1]
	v_pk_fma_f32 v[230:231], v[132:133], v[246:247], v[230:231] op_sel_hi:[0,1,1]
	v_cvt_pk_f32_fp8_sdwa v[242:243], v62 src0_sel:WORD_1
	v_cvt_pk_f32_fp8_e32 v[244:245], v63
	v_cvt_pk_f32_fp8_sdwa v[246:247], v63 src0_sel:WORD_1
	v_pk_fma_f32 v[232:233], v[132:133], v[240:241], v[232:233] op_sel_hi:[0,1,1]
	s_waitcnt vmcnt(16)
; DI void up_issue(u32x4 (&W)[16], u32 (&pj)[16], const u32* pl, const unsigned char* wbase, int grp) {
; #pragma unroll
;   for (int j = 0; j < 16; ++j) {
;     pj[j] = pl[8 * j + grp];
;     W[j] = *(const u32x4*)(wbase + (size_t)(pj[j] >> 16) * 1024);
;   }
; DI void up_math(const u32x4 (&W)[16], const u32 (&pj)[16], float* __restrict__ yrow, int lane) {
;     ...
;   const bool b5 = lane & 32, b4 = lane & 16, b3 = lane & 8;
;   f2 q4[4];
; #pragma unroll
;   for (int i = 0; i < 4; ++i) {
;     f2 snd = b5 ? y[i] : y[i + 4]; f2 kp = b5 ? y[i + 4] : y[i];
;     q4[i] = f2{kp.x + __shfl_xor(snd.x, 32), kp.y + __shfl_xor(snd.y, 32)};
;   }
;   f2 r2[2];
; #pragma unroll
;   for (int i = 0; i < 2; ++i) {
;     f2 snd = b4 ? q4[i] : q4[i + 2]; f2 kp = b4 ? q4[i + 2] : q4[i];
;     r2[i] = f2{kp.x + __shfl_xor(snd.x, 16), kp.y + __shfl_xor(snd.y, 16)};
;   }
;   f2 a;
;   { f2 snd = b3 ? r2[0] : r2[1]; f2 kp = b3 ? r2[1] : r2[0]; a = f2{kp.x + __shfl_xor(snd.x, 8), kp.y + __shfl_xor(snd.y, 8)}; }
;   const int ci = (b5 ? 4 : 0) + (b4 ? 2 : 0) + (b3 ? 1 : 0);
;   *(float2*)(yrow + (lane & 7) * 16 + 2 * ci) = make_float2(a.x, a.y);
	v_cvt_pk_f32_fp8_e32 v[240:241], v64
	v_pk_fma_f32 v[234:235], v[132:133], v[242:243], v[234:235] op_sel_hi:[0,1,1]
	v_pk_fma_f32 v[236:237], v[132:133], v[244:245], v[236:237] op_sel_hi:[0,1,1]
	v_pk_fma_f32 v[238:239], v[132:133], v[246:247], v[238:239] op_sel_hi:[0,1,1]
	v_cvt_pk_f32_fp8_sdwa v[242:243], v64 src0_sel:WORD_1
	v_cvt_pk_f32_fp8_e32 v[244:245], v65
	v_cvt_pk_f32_fp8_sdwa v[246:247], v65 src0_sel:WORD_1
	v_lshlrev_b32_e32 v132, 16, v195
	v_pk_fma_f32 v[216:217], v[132:133], v[240:241], v[216:217] op_sel_hi:[0,1,1]
	v_cvt_pk_f32_fp8_e32 v[240:241], v66
	v_pk_fma_f32 v[226:227], v[132:133], v[242:243], v[226:227] op_sel_hi:[0,1,1]
	v_pk_fma_f32 v[228:229], v[132:133], v[244:245], v[228:229] op_sel_hi:[0,1,1]
	v_pk_fma_f32 v[230:231], v[132:133], v[246:247], v[230:231] op_sel_hi:[0,1,1]
	v_cvt_pk_f32_fp8_sdwa v[242:243], v66 src0_sel:WORD_1
	v_cvt_pk_f32_fp8_e32 v[244:245], v67
	v_cvt_pk_f32_fp8_sdwa v[246:247], v67 src0_sel:WORD_1
	v_pk_fma_f32 v[232:233], v[132:133], v[240:241], v[232:233] op_sel_hi:[0,1,1]
	v_pk_fma_f32 v[234:235], v[132:133], v[242:243], v[234:235] op_sel_hi:[0,1,1]
	v_pk_fma_f32 v[236:237], v[132:133], v[244:245], v[236:237] op_sel_hi:[0,1,1]
	v_pk_fma_f32 v[238:239], v[132:133], v[246:247], v[238:239] op_sel_hi:[0,1,1]
	s_nop 1
	v_permlane32_swap_b32_e32 v216, v232
	v_permlane32_swap_b32_e32 v217, v233
	v_permlane32_swap_b32_e32 v228, v236
	v_permlane32_swap_b32_e32 v229, v237
	v_permlane32_swap_b32_e32 v226, v234
	v_permlane32_swap_b32_e32 v227, v235
	v_permlane32_swap_b32_e32 v230, v238
	v_permlane32_swap_b32_e32 v231, v239
	v_pk_add_f32 v[216:217], v[216:217], v[232:233]
	v_pk_add_f32 v[228:229], v[228:229], v[236:237]
	v_pk_add_f32 v[226:227], v[226:227], v[234:235]
	v_pk_add_f32 v[230:231], v[230:231], v[238:239]
	s_nop 1
	v_permlane16_swap_b32_e32 v216, v228
	v_permlane16_swap_b32_e32 v217, v229
	v_permlane16_swap_b32_e32 v226, v230
	v_permlane16_swap_b32_e32 v227, v231
	v_pk_add_f32 v[216:217], v[216:217], v[228:229]
	v_pk_add_f32 v[226:227], v[226:227], v[230:231]
	s_nop 1
	v_add_f32_dpp v216, v216, v216 row_shl:8 row_mask:0xf bank_mask:0x3
	v_add_f32_dpp v217, v217, v217 row_shl:8 row_mask:0xf bank_mask:0x3
	v_add_f32_dpp v216, v226, v226 row_shr:8 row_mask:0xf bank_mask:0xc
	v_add_f32_dpp v217, v227, v227 row_shr:8 row_mask:0xf bank_mask:0xc
	global_store_dwordx2 v[188:189], v[216:217], off
	s_cmp_gt_u32 s36, 13
	s_cselect_b64 s[28:29], -1, 0
	s_and_b64 vcc, exec, s[28:29]
	s_cbranch_vccnz .LBB0_1649
	ds_read2_b32 v[178:179], v145 offset0:128 offset1:136
	ds_read2_b32 v[180:181], v145 offset0:144 offset1:152
	s_waitcnt lgkmcnt(1)
	v_lshlrev_b32_sdwa v132, v215, v178 dst_sel:DWORD dst_unused:UNUSED_PAD src0_sel:DWORD src1_sel:WORD_1
	v_lshl_add_u64 v[4:5], v[174:175], 0, v[132:133]
	v_lshlrev_b32_sdwa v132, v215, v179 dst_sel:DWORD dst_unused:UNUSED_PAD src0_sel:DWORD src1_sel:WORD_1
	v_lshl_add_u64 v[8:9], v[174:175], 0, v[132:133]
	s_waitcnt lgkmcnt(0)
	v_lshlrev_b32_sdwa v132, v215, v180 dst_sel:DWORD dst_unused:UNUSED_PAD src0_sel:DWORD src1_sel:WORD_1
	global_load_dwordx4 v[4:7], v[4:5], off
	s_nop 0
	global_load_dwordx4 v[8:11], v[8:9], off
	v_lshl_add_u64 v[12:13], v[174:175], 0, v[132:133]
	ds_read2_b32 v[182:183], v145 offset0:160 offset1:168
	v_lshlrev_b32_sdwa v132, v215, v181 dst_sel:DWORD dst_unused:UNUSED_PAD src0_sel:DWORD src1_sel:WORD_1
	v_lshl_add_u64 v[16:17], v[174:175], 0, v[132:133]
	global_load_dwordx4 v[12:15], v[12:13], off
	s_nop 0
	global_load_dwordx4 v[16:19], v[16:17], off
	ds_read2_b32 v[184:185], v145 offset0:176 offset1:184
	s_waitcnt lgkmcnt(1)
	v_lshlrev_b32_sdwa v132, v215, v182 dst_sel:DWORD dst_unused:UNUSED_PAD src0_sel:DWORD src1_sel:WORD_1
	v_lshl_add_u64 v[20:21], v[174:175], 0, v[132:133]
	v_lshlrev_b32_sdwa v132, v215, v183 dst_sel:DWORD dst_unused:UNUSED_PAD src0_sel:DWORD src1_sel:WORD_1
	v_lshl_add_u64 v[24:25], v[174:175], 0, v[132:133]
	s_waitcnt lgkmcnt(0)
	v_lshlrev_b32_sdwa v132, v215, v184 dst_sel:DWORD dst_unused:UNUSED_PAD src0_sel:DWORD src1_sel:WORD_1
	global_load_dwordx4 v[20:23], v[20:21], off
	s_nop 0
	global_load_dwordx4 v[24:27], v[24:25], off
	v_lshl_add_u64 v[28:29], v[174:175], 0, v[132:133]
	ds_read2_b32 v[186:187], v145 offset0:192 offset1:200
	v_lshlrev_b32_sdwa v132, v215, v185 dst_sel:DWORD dst_unused:UNUSED_PAD src0_sel:DWORD src1_sel:WORD_1
	v_lshl_add_u64 v[32:33], v[174:175], 0, v[132:133]
	global_load_dwordx4 v[28:31], v[28:29], off
	s_nop 0
	global_load_dwordx4 v[32:35], v[32:33], off
	ds_read2_b32 v[190:191], v145 offset0:208 offset1:216
	s_waitcnt lgkmcnt(1)
	v_lshlrev_b32_sdwa v132, v215, v186 dst_sel:DWORD dst_unused:UNUSED_PAD src0_sel:DWORD src1_sel:WORD_1
	v_lshl_add_u64 v[36:37], v[174:175], 0, v[132:133]
	v_lshlrev_b32_sdwa v132, v215, v187 dst_sel:DWORD dst_unused:UNUSED_PAD src0_sel:DWORD src1_sel:WORD_1
	v_lshl_add_u64 v[40:41], v[174:175], 0, v[132:133]
	s_waitcnt lgkmcnt(0)
	v_lshlrev_b32_sdwa v132, v215, v190 dst_sel:DWORD dst_unused:UNUSED_PAD src0_sel:DWORD src1_sel:WORD_1
	global_load_dwordx4 v[36:39], v[36:37], off
	s_nop 0
	global_load_dwordx4 v[40:43], v[40:41], off
	v_lshl_add_u64 v[44:45], v[174:175], 0, v[132:133]
	ds_read2_b32 v[192:193], v145 offset0:224 offset1:232
	v_lshlrev_b32_sdwa v132, v215, v191 dst_sel:DWORD dst_unused:UNUSED_PAD src0_sel:DWORD src1_sel:WORD_1
	v_lshl_add_u64 v[48:49], v[174:175], 0, v[132:133]
	global_load_dwordx4 v[44:47], v[44:45], off
	s_nop 0
	global_load_dwordx4 v[48:51], v[48:49], off
	ds_read2_b32 v[194:195], v145 offset0:240 offset1:248
	s_waitcnt lgkmcnt(1)
	v_lshlrev_b32_sdwa v132, v215, v192 dst_sel:DWORD dst_unused:UNUSED_PAD src0_sel:DWORD src1_sel:WORD_1
	v_lshl_add_u64 v[52:53], v[174:175], 0, v[132:133]
	v_lshlrev_b32_sdwa v132, v215, v193 dst_sel:DWORD dst_unused:UNUSED_PAD src0_sel:DWORD src1_sel:WORD_1
	v_lshl_add_u64 v[56:57], v[174:175], 0, v[132:133]
	s_waitcnt lgkmcnt(0)
	v_lshlrev_b32_sdwa v132, v215, v194 dst_sel:DWORD dst_unused:UNUSED_PAD src0_sel:DWORD src1_sel:WORD_1
	v_lshl_add_u64 v[60:61], v[174:175], 0, v[132:133]
	v_lshlrev_b32_sdwa v132, v215, v195 dst_sel:DWORD dst_unused:UNUSED_PAD src0_sel:DWORD src1_sel:WORD_1
	v_lshl_add_u64 v[64:65], v[174:175], 0, v[132:133]
	global_load_dwordx4 v[52:55], v[52:53], off
	s_nop 0
	global_load_dwordx4 v[56:59], v[56:57], off
	s_nop 0
	global_load_dwordx4 v[60:63], v[60:61], off
	s_nop 0
	global_load_dwordx4 v[64:67], v[64:65], off
	s_branch .LBB0_1649
